# sort quad stages as sub_co_dpp + s_xor + cndmask_dpp (2 VALU); bpermute lane offsets folded into offset field
# baseline (speedup 1.0000x reference)
.LBB0_328:
	v_ashrrev_i32_e32 v117, 31, v116
	v_lshlrev_b64 v[0:1], 11, v[116:117]
	v_lshl_add_u64 v[134:135], v[122:123], 0, v[0:1]
	global_load_dwordx4 v[12:15], v[134:135], off
	global_load_dwordx4 v[0:3], v[134:135], off offset:16
	v_readlane_b32 s2, v249, 30
	v_readlane_b32 s3, v249, 31
	s_load_dwordx2 s[2:3], s[2:3], 0x180
	v_lshlrev_b64 v[136:137], 10, v[116:117]
	v_mov_b32_e32 v131, v80
	v_mov_b32_e32 v133, v80
	s_movk_i32 s43, 0x80
	s_waitcnt lgkmcnt(0)
	v_lshl_add_u64 v[4:5], s[2:3], 0, v[136:137]
	v_lshl_add_u64 v[18:19], v[4:5], 0, v[130:131]
	v_lshl_add_u64 v[16:17], v[4:5], 0, v[132:133]
	global_load_dword v26, v[16:17], off offset:64
	global_load_dword v28, v[18:19], off
	global_load_dword v25, v[16:17], off offset:192
	global_load_dword v27, v[18:19], off offset:128
	global_load_dwordx4 v[4:7], v[134:135], off offset:48
	global_load_dwordx4 v[8:11], v[134:135], off offset:32
	global_load_dword v21, v[18:19], off offset:256
	global_load_dword v23, v[18:19], off offset:384
	global_load_dword v22, v[18:19], off offset:512
	global_load_dword v24, v[18:19], off offset:640
	global_load_dword v20, v[18:19], off offset:768
	s_nop 0
	global_load_dword v18, v[18:19], off offset:896
	s_nop 0
	global_load_dword v117, v[16:17], off offset:320
	global_load_dword v31, v[16:17], off offset:448
	global_load_dword v30, v[16:17], off offset:576
	global_load_dword v29, v[16:17], off offset:704
	global_load_dword v19, v[16:17], off offset:832
	s_nop 0
	global_load_dword v16, v[16:17], off offset:960
	s_movk_i32 s44, 0x3f80
	v_mov_b32_e32 v176, 0
	v_mov_b32_e32 v177, v176
	v_mov_b32_e32 v216, v176
	v_mov_b32_e32 v217, v176
	v_mov_b32_e32 v214, v176
	v_mov_b32_e32 v215, v176
	v_mov_b32_e32 v212, v176
	v_mov_b32_e32 v213, v176
	v_mov_b32_e32 v210, v176
	v_mov_b32_e32 v211, v176
	v_mov_b32_e32 v208, v176
	v_mov_b32_e32 v209, v176
	v_mov_b32_e32 v206, v176
	v_mov_b32_e32 v207, v176
	v_mov_b32_e32 v204, v176
	v_mov_b32_e32 v205, v176
	v_mov_b32_e32 v202, v176
	v_mov_b32_e32 v203, v176
	v_mov_b32_e32 v200, v176
	v_mov_b32_e32 v201, v176
	v_mov_b32_e32 v198, v176
	v_mov_b32_e32 v199, v176
	v_mov_b32_e32 v196, v176
	v_mov_b32_e32 v197, v176
	v_mov_b32_e32 v194, v176
	v_mov_b32_e32 v195, v176
	v_mov_b32_e32 v192, v176
	v_mov_b32_e32 v193, v176
	v_mov_b32_e32 v190, v176
	v_mov_b32_e32 v191, v176
	v_mov_b32_e32 v188, v176
	v_mov_b32_e32 v189, v176
	s_waitcnt vmcnt(17)
	v_cmp_lt_i32_e32 vcc, -1, v26
	s_waitcnt vmcnt(13)
	v_lshlrev_b32_e32 v160, 16, v4
	v_lshlrev_b32_e32 v152, 16, v12
	v_lshlrev_b32_e32 v174, 16, v1
	v_and_b32_e32 v143, 0xffff0000, v1
	v_cndmask_b32_e64 v1, v232, -1, vcc
	v_cmp_lt_i32_e32 vcc, -1, v28
	v_and_b32_e32 v150, 0xffff0000, v12
	v_lshlrev_b32_e32 v148, 16, v14
	v_cndmask_b32_e64 v12, v232, -1, vcc
	v_cmp_lt_i32_e32 vcc, -1, v25
	v_and_b32_e32 v146, 0xffff0000, v14
	v_lshlrev_b32_e32 v172, 16, v15
	v_cndmask_b32_e64 v17, v232, -1, vcc
	v_cmp_lt_i32_e32 vcc, -1, v27
	v_and_b32_e32 v147, 0xffff0000, v15
	v_lshlrev_b32_e32 v144, 16, v0
	v_and_b32_e32 v142, 0xffff0000, v0
	v_lshlrev_b32_e32 v140, 16, v2
	v_and_b32_e32 v138, 0xffff0000, v2
	v_and_b32_e32 v0, 0xffffff80, v26
	v_and_b32_e32 v2, 0xffffff80, v28
	v_and_b32_e32 v14, 0xffffff80, v25
	v_and_b32_e32 v15, 0xffffff80, v27
	v_cndmask_b32_e64 v32, v232, -1, vcc
	v_lshlrev_b32_e32 v170, 16, v13
	v_and_b32_e32 v151, 0xffff0000, v13
	v_xor_b32_e32 v1, v1, v0
	v_xor_b32_e32 v13, v12, v2
	v_xor_b32_e32 v0, v17, v14
	v_xor_b32_e32 v12, v32, v15
	v_pk_add_f32 v[0:1], v[12:13], v[0:1]
	v_lshlrev_b32_e32 v178, 16, v3
	v_or_b32_e32 v2, 0x80000000, v1
	v_not_b32_e32 v12, v1
	v_cmp_gt_i32_e32 vcc, 0, v1
	v_and_b32_e32 v139, 0xffff0000, v3
	s_waitcnt vmcnt(12)
	v_lshlrev_b32_e32 v168, 16, v8
	v_cndmask_b32_e32 v2, v2, v12, vcc
	v_and_b32_e32 v2, 0xffffffc0, v2
	v_bitop3_b32 v2, v2, 63, v81 bitop3:0x36
	v_cndmask_b32_e64 v2, 0, v2, s[10:11]
	v_and_b32_e32 v166, 0xffff0000, v8
	v_readlane_b32 s3, v2, 1
	v_readlane_b32 s24, v2, 2
	v_readlane_b32 s26, v2, 4
	v_cmp_gt_u32_e32 vcc, s3, v2
	v_readlane_b32 s30, v2, 6
	v_readlane_b32 s34, v2, 8
	v_cndmask_b32_e64 v12, 0, 1, vcc
	v_cmp_gt_u32_e32 vcc, s24, v2
	v_readlane_b32 s2, v2, 0
	v_readlane_b32 s25, v2, 3
	v_cndmask_b32_e64 v13, 0, 1, vcc
	v_cmp_gt_u32_e32 vcc, s26, v2
	v_readlane_b32 s27, v2, 5
	v_readlane_b32 s31, v2, 7
	v_cndmask_b32_e64 v14, 0, 1, vcc
	v_cmp_gt_u32_e32 vcc, s30, v2
	v_and_b32_e32 v158, 0xffff0000, v4
	v_lshlrev_b32_e32 v184, 16, v5
	v_cndmask_b32_e64 v15, 0, 1, vcc
	v_cmp_gt_u32_e32 vcc, s34, v2
	v_and_b32_e32 v159, 0xffff0000, v5
	v_lshlrev_b32_e32 v156, 16, v6
	v_cndmask_b32_e64 v17, 0, 1, vcc
	v_cmp_gt_u32_e32 vcc, s2, v2
	v_readlane_b32 s2, v2, 9
	v_and_b32_e32 v154, 0xffff0000, v6
	v_addc_co_u32_e32 v12, vcc, 0, v12, vcc
	v_cmp_gt_u32_e32 vcc, s25, v2
	v_lshlrev_b32_e32 v5, 7, v28
	v_and_b32_e32 v6, 0x7f, v26
	v_addc_co_u32_e32 v12, vcc, v12, v13, vcc
	v_cmp_gt_u32_e32 vcc, s27, v2
	v_and_or_b32 v5, v5, s44, v6
	v_lshlrev_b32_e32 v186, 16, v7
	v_addc_co_u32_e32 v12, vcc, v12, v14, vcc
	v_cmp_gt_u32_e32 vcc, s31, v2
	v_and_b32_e32 v155, 0xffff0000, v7
	v_lshlrev_b32_e32 v164, 16, v10
	v_addc_co_u32_e32 v12, vcc, v12, v15, vcc
	v_cmp_gt_u32_e32 vcc, s2, v2
	v_readlane_b32 s2, v2, 10
	v_and_b32_e32 v162, 0xffff0000, v10
	v_addc_co_u32_e32 v12, vcc, v12, v17, vcc
	v_cmp_gt_u32_e32 vcc, s2, v2
	v_readlane_b32 s2, v2, 11
	v_lshlrev_b32_e32 v182, 16, v11
	v_cndmask_b32_e64 v13, 0, 1, vcc
	v_cmp_gt_u32_e32 vcc, s2, v2
	v_readlane_b32 s2, v2, 12
	v_and_b32_e32 v163, 0xffff0000, v11
	v_addc_co_u32_e32 v12, vcc, v12, v13, vcc
	v_cmp_gt_u32_e32 vcc, s2, v2
	v_readlane_b32 s2, v2, 13
	v_not_b32_e32 v17, v0
	v_cndmask_b32_e64 v13, 0, 1, vcc
	v_cmp_gt_u32_e32 vcc, s2, v2
	v_readlane_b32 s2, v2, 14
	v_lshlrev_b32_e32 v180, 16, v9
	v_addc_co_u32_e32 v12, vcc, v12, v13, vcc
	v_cmp_gt_u32_e32 vcc, s2, v2
	v_readlane_b32 s2, v2, 15
	v_and_b32_e32 v167, 0xffff0000, v9
	v_cndmask_b32_e64 v13, 0, 1, vcc
	v_cmp_gt_u32_e32 vcc, s2, v2
	v_readlane_b32 s2, v2, 16
	v_and_b32_e32 v9, 0x7f, v25
	v_addc_co_u32_e32 v12, vcc, v12, v13, vcc
	v_cmp_gt_u32_e32 vcc, s2, v2
	v_readlane_b32 s2, v2, 17
	s_mov_b32 s24, 0
	v_cndmask_b32_e64 v13, 0, 1, vcc
	v_cmp_gt_u32_e32 vcc, s2, v2
	v_readlane_b32 s2, v2, 18
	v_mov_b32_e32 v153, v150
	v_addc_co_u32_e32 v12, vcc, v12, v13, vcc
	v_cmp_gt_u32_e32 vcc, s2, v2
	v_readlane_b32 s2, v2, 19
	v_mov_b32_e32 v171, v151
	v_cndmask_b32_e64 v13, 0, 1, vcc
	v_cmp_gt_u32_e32 vcc, s2, v2
	v_readlane_b32 s2, v2, 20
	v_mov_b32_e32 v149, v146
	v_addc_co_u32_e32 v12, vcc, v12, v13, vcc
	v_cmp_gt_u32_e32 vcc, s2, v2
	v_readlane_b32 s2, v2, 21
	v_mov_b32_e32 v173, v147
	v_cndmask_b32_e64 v13, 0, 1, vcc
	v_cmp_gt_u32_e32 vcc, s2, v2
	v_readlane_b32 s2, v2, 22
	v_mov_b32_e32 v145, v142
	v_addc_co_u32_e32 v12, vcc, v12, v13, vcc
	v_cmp_gt_u32_e32 vcc, s2, v2
	v_readlane_b32 s2, v2, 23
	v_mov_b32_e32 v175, v143
	v_cndmask_b32_e64 v13, 0, 1, vcc
	v_cmp_gt_u32_e32 vcc, s2, v2
	v_readlane_b32 s2, v2, 24
	v_mov_b32_e32 v141, v138
	v_addc_co_u32_e32 v12, vcc, v12, v13, vcc
	v_cmp_gt_u32_e32 vcc, s2, v2
	v_readlane_b32 s2, v2, 25
	v_mov_b32_e32 v179, v139
	v_cndmask_b32_e64 v13, 0, 1, vcc
	v_cmp_gt_u32_e32 vcc, s2, v2
	v_readlane_b32 s2, v2, 26
	v_mov_b32_e32 v169, v166
	v_addc_co_u32_e32 v12, vcc, v12, v13, vcc
	v_cmp_gt_u32_e32 vcc, s2, v2
	v_readlane_b32 s2, v2, 27
	v_mov_b32_e32 v181, v167
	v_cndmask_b32_e64 v13, 0, 1, vcc
	v_cmp_gt_u32_e32 vcc, s2, v2
	v_readlane_b32 s2, v2, 28
	v_mov_b32_e32 v165, v162
	v_addc_co_u32_e32 v12, vcc, v12, v13, vcc
	v_cmp_gt_u32_e32 vcc, s2, v2
	v_readlane_b32 s2, v2, 29
	v_mov_b32_e32 v183, v163
	v_cndmask_b32_e64 v13, 0, 1, vcc
	v_cmp_gt_u32_e32 vcc, s2, v2
	v_readlane_b32 s2, v2, 30
	v_mov_b32_e32 v161, v158
	v_addc_co_u32_e32 v12, vcc, v12, v13, vcc
	v_cmp_gt_u32_e32 vcc, s2, v2
	v_readlane_b32 s2, v2, 31
	v_mov_b32_e32 v185, v159
	v_cndmask_b32_e64 v13, 0, 1, vcc
	v_cmp_gt_u32_e32 vcc, s2, v2
	v_readlane_b32 s2, v2, 32
	v_mov_b32_e32 v157, v154
	v_addc_co_u32_e32 v12, vcc, v12, v13, vcc
	v_cmp_gt_u32_e32 vcc, s2, v2
	v_readlane_b32 s2, v2, 33
	v_mov_b32_e32 v187, v155
	v_cndmask_b32_e64 v13, 0, 1, vcc
	v_cmp_gt_u32_e32 vcc, s2, v2
	v_readlane_b32 s2, v2, 34
	s_nop 0
	v_addc_co_u32_e32 v12, vcc, v12, v13, vcc
	v_cmp_gt_u32_e32 vcc, s2, v2
	v_readlane_b32 s2, v2, 35
	s_nop 0
	v_cndmask_b32_e64 v13, 0, 1, vcc
	v_cmp_gt_u32_e32 vcc, s2, v2
	v_readlane_b32 s2, v2, 36
	s_nop 0
	v_addc_co_u32_e32 v12, vcc, v12, v13, vcc
	v_cmp_gt_u32_e32 vcc, s2, v2
	v_readlane_b32 s2, v2, 37
	s_nop 0
	v_cndmask_b32_e64 v13, 0, 1, vcc
	v_cmp_gt_u32_e32 vcc, s2, v2
	v_readlane_b32 s2, v2, 38
	s_nop 0
	v_addc_co_u32_e32 v12, vcc, v12, v13, vcc
	v_cmp_gt_u32_e32 vcc, s2, v2
	v_readlane_b32 s2, v2, 39
	s_nop 0
	v_cndmask_b32_e64 v13, 0, 1, vcc
	v_cmp_gt_u32_e32 vcc, s2, v2
	v_readlane_b32 s2, v2, 40
	s_nop 0
	v_addc_co_u32_e32 v12, vcc, v12, v13, vcc
	v_cmp_gt_u32_e32 vcc, s2, v2
	v_readlane_b32 s2, v2, 41
	s_nop 0
	v_cndmask_b32_e64 v13, 0, 1, vcc
	v_cmp_gt_u32_e32 vcc, s2, v2
	v_readlane_b32 s2, v2, 42
	s_nop 0
	v_addc_co_u32_e32 v12, vcc, v12, v13, vcc
	v_cmp_gt_u32_e32 vcc, s2, v2
	v_readlane_b32 s2, v2, 43
	s_nop 0
	v_cndmask_b32_e64 v13, 0, 1, vcc
	v_cmp_gt_u32_e32 vcc, s2, v2
	v_readlane_b32 s2, v2, 44
	s_nop 0
	v_addc_co_u32_e32 v12, vcc, v12, v13, vcc
	v_cmp_gt_u32_e32 vcc, s2, v2
	v_readlane_b32 s2, v2, 45
	s_nop 0
	v_cndmask_b32_e64 v13, 0, 1, vcc
	v_cmp_gt_u32_e32 vcc, s2, v2
	v_readlane_b32 s2, v2, 46
	s_nop 0
	v_addc_co_u32_e32 v12, vcc, v12, v13, vcc
	v_cmp_gt_u32_e32 vcc, s2, v2
	v_readlane_b32 s2, v2, 47
	s_nop 0
	v_cndmask_b32_e64 v13, 0, 1, vcc
	v_cmp_gt_u32_e32 vcc, s2, v2
	v_readlane_b32 s2, v2, 48
	s_nop 0
	v_addc_co_u32_e32 v12, vcc, v12, v13, vcc
	v_cmp_gt_u32_e32 vcc, s2, v2
	v_readlane_b32 s2, v2, 49
	s_nop 0
	v_cndmask_b32_e64 v13, 0, 1, vcc
	v_cmp_gt_u32_e32 vcc, s2, v2
	s_nop 1
	v_addc_co_u32_e32 v2, vcc, v12, v13, vcc
	v_lshlrev_b32_e32 v13, 3, v2
	v_lshlrev_b32_e32 v12, 7, v2
	v_and_b32_e32 v13, 0x70, v13
	v_and_or_b32 v12, v12, s43, v13
	v_cmp_gt_u32_e32 vcc, 16, v2
	s_nop 1
	v_cndmask_b32_e32 v2, 4, v12, vcc
	ds_permute_b32 v1, v2, v1
	ds_permute_b32 v2, v2, v5
	s_waitcnt lgkmcnt(1)
	v_readlane_b32 s2, v1, 0
	s_nop 1
	v_subrev_f32_e32 v1, s2, v1
	v_mul_f32_e32 v1, 0x3fb8aa3b, v1
	v_exp_f32_e32 v1, v1
	s_waitcnt lgkmcnt(0)
	v_readlane_b32 s25, v2, 4
	v_readlane_b32 s26, v2, 36
	v_readlane_b32 s27, v2, 8
	v_cndmask_b32_e64 v1, 0, v1, s[12:13]
	ds_bpermute_b32 v3, v240, v1
	v_readlane_b32 s30, v2, 40
	v_readlane_b32 s31, v2, 12
	v_readlane_b32 s34, v2, 44
	v_readlane_b32 s35, v2, 16
	s_waitcnt lgkmcnt(0)
	v_add_f32_e32 v3, v1, v3
	ds_bpermute_b32 v8, v241, v3
	v_readlane_b32 s36, v2, 48
	v_readlane_b32 s37, v2, 20
	v_readlane_b32 s38, v2, 52
	v_readlane_b32 s39, v2, 24
	s_waitcnt lgkmcnt(0)
	v_add_f32_e32 v3, v3, v8
	ds_bpermute_b32 v4, v242, v3
	v_readlane_b32 s40, v2, 56
	v_readlane_b32 s41, v2, 28
	v_readlane_b32 s42, v2, 60
	v_lshlrev_b32_e32 v8, 7, v27
	s_waitcnt lgkmcnt(0)
	v_add_f32_e32 v3, v3, v4
	ds_bpermute_b32 v4, v243, v3
	v_and_or_b32 v8, v8, s44, v9
	s_waitcnt lgkmcnt(0)
	v_add_f32_e32 v3, v3, v4
	v_div_scale_f32 v4, s[2:3], v3, v3, v1
	v_rcp_f32_e32 v6, v4
	v_readlane_b32 s2, v2, 0
	v_readlane_b32 s3, v2, 32
	v_fma_f32 v5, -v4, v6, 1.0
	v_fmac_f32_e32 v6, v5, v6
	v_div_scale_f32 v5, vcc, v1, v3, v1
	v_mul_f32_e32 v7, v5, v6
	v_fma_f32 v10, -v4, v7, v5
	v_fmac_f32_e32 v7, v10, v6
	v_fma_f32 v4, -v4, v7, v5
	v_div_fmas_f32 v4, v4, v6, v7
	v_div_fixup_f32 v3, v4, v3, v1
	v_mov_b32_e32 v1, s2
	v_mov_b32_e32 v4, s3
	v_cndmask_b32_e64 v1, v1, v4, s[6:7]
	v_mad_i64_i32 v[4:5], s[2:3], v1, s28, v[118:119]
	global_load_dwordx2 v[36:37], v[4:5], off offset:16
	global_load_dwordx4 v[32:35], v[4:5], off
	v_mov_b32_e32 v4, s25
	v_mov_b32_e32 v5, s26
	v_cndmask_b32_e64 v6, v4, v5, s[6:7]
	v_mad_i64_i32 v[4:5], s[2:3], v6, s28, v[118:119]
	global_load_dwordx2 v[42:43], v[4:5], off offset:16
	global_load_dwordx4 v[38:41], v[4:5], off
	v_mov_b32_e32 v4, s27
	v_mov_b32_e32 v5, s30
	v_cndmask_b32_e64 v10, v4, v5, s[6:7]
	v_mad_i64_i32 v[4:5], s[2:3], v10, s28, v[118:119]
	global_load_dwordx2 v[48:49], v[4:5], off offset:16
	global_load_dwordx4 v[44:47], v[4:5], off
	v_mov_b32_e32 v4, s31
	v_mov_b32_e32 v5, s34
	v_cndmask_b32_e64 v11, v4, v5, s[6:7]
	v_mad_i64_i32 v[4:5], s[2:3], v11, s28, v[118:119]
	global_load_dwordx2 v[54:55], v[4:5], off offset:16
	global_load_dwordx4 v[50:53], v[4:5], off
	v_mov_b32_e32 v4, s35
	v_mov_b32_e32 v5, s36
	v_cndmask_b32_e64 v12, v4, v5, s[6:7]
	v_mad_i64_i32 v[4:5], s[2:3], v12, s28, v[118:119]
	global_load_dwordx2 v[60:61], v[4:5], off offset:16
	global_load_dwordx4 v[56:59], v[4:5], off
	v_mov_b32_e32 v4, s37
	v_mov_b32_e32 v5, s38
	v_cndmask_b32_e64 v13, v4, v5, s[6:7]
	v_mad_i64_i32 v[4:5], s[2:3], v13, s28, v[118:119]
	global_load_dwordx2 v[66:67], v[4:5], off offset:16
	global_load_dwordx4 v[62:65], v[4:5], off
	v_mov_b32_e32 v4, s39
	v_mov_b32_e32 v5, s40
	v_cndmask_b32_e64 v14, v4, v5, s[6:7]
	v_mad_i64_i32 v[4:5], s[2:3], v14, s28, v[118:119]
	global_load_dwordx2 v[72:73], v[4:5], off offset:16
	global_load_dwordx4 v[68:71], v[4:5], off
	v_mov_b32_e32 v4, s41
	v_mov_b32_e32 v5, s42
	v_cndmask_b32_e64 v15, v4, v5, s[6:7]
	v_mad_i64_i32 v[4:5], s[2:3], v15, s28, v[118:119]
	global_load_dwordx2 v[78:79], v[4:5], off offset:16
	global_load_dwordx4 v[74:77], v[4:5], off
	v_mad_i64_i32 v[4:5], s[2:3], v1, s28, v[120:121]
	v_or_b32_e32 v1, 0x80000000, v0
	v_cmp_gt_i32_e32 vcc, 0, v0
	v_mad_i64_i32 v[6:7], s[2:3], v6, s28, v[120:121]
	s_nop 0
	v_cndmask_b32_e32 v1, v1, v17, vcc
	v_and_b32_e32 v1, 0xffffffc0, v1
	v_cndmask_b32_e64 v1, 0, v1, s[10:11]
	v_bitop3_b32 v1, v1, 63, v81 bitop3:0x36
	global_load_dwordx4 v[110:113], v[4:5], off offset:768
	global_load_dwordx4 v[106:109], v[6:7], off offset:768
	s_nop 1
	v_sub_co_u32_dpp v250, vcc, v1, v1 quad_perm:[1,0,3,2] row_mask:0xf bank_mask:0xf
	s_xor_b32 vcc_lo, vcc_lo, 0xaaaaaaaa
	s_xor_b32 vcc_hi, vcc_hi, 0xaaaaaaaa
	v_cndmask_b32_dpp v17, v1, v1, vcc quad_perm:[1,0,3,2] row_mask:0xf bank_mask:0xf
	s_nop 1
	v_sub_co_u32_dpp v250, vcc, v17, v17 quad_perm:[3,2,1,0] row_mask:0xf bank_mask:0xf
	s_xor_b32 vcc_lo, vcc_lo, 0xcccccccc
	s_xor_b32 vcc_hi, vcc_hi, 0xcccccccc
	v_cndmask_b32_dpp v1, v17, v17, vcc quad_perm:[3,2,1,0] row_mask:0xf bank_mask:0xf
	s_nop 1
	v_sub_co_u32_dpp v250, vcc, v1, v1 quad_perm:[1,0,3,2] row_mask:0xf bank_mask:0xf
	s_xor_b32 vcc_lo, vcc_lo, 0xaaaaaaaa
	s_xor_b32 vcc_hi, vcc_hi, 0xaaaaaaaa
	v_cndmask_b32_dpp v17, v1, v1, vcc quad_perm:[1,0,3,2] row_mask:0xf bank_mask:0xf
	s_nop 1
	v_max_u32_dpp v1, v17, v17 row_half_mirror row_mask:0xf bank_mask:0x5
	v_min_u32_dpp v1, v17, v17 row_half_mirror row_mask:0xf bank_mask:0xa
	s_nop 1
	v_sub_co_u32_dpp v250, vcc, v1, v1 quad_perm:[2,3,0,1] row_mask:0xf bank_mask:0xf
	s_xor_b32 vcc_lo, vcc_lo, 0xcccccccc
	s_xor_b32 vcc_hi, vcc_hi, 0xcccccccc
	v_cndmask_b32_dpp v17, v1, v1, vcc quad_perm:[2,3,0,1] row_mask:0xf bank_mask:0xf
	s_nop 1
	v_sub_co_u32_dpp v250, vcc, v17, v17 quad_perm:[1,0,3,2] row_mask:0xf bank_mask:0xf
	s_xor_b32 vcc_lo, vcc_lo, 0xaaaaaaaa
	s_xor_b32 vcc_hi, vcc_hi, 0xaaaaaaaa
	v_cndmask_b32_dpp v1, v17, v17, vcc quad_perm:[1,0,3,2] row_mask:0xf bank_mask:0xf
	s_nop 1
	v_max_u32_dpp v17, v1, v1 row_mirror row_mask:0xf bank_mask:0x3
	v_min_u32_dpp v17, v1, v1 row_mirror row_mask:0xf bank_mask:0xc
	s_nop 1
	v_max_u32_dpp v1, v17, v17 row_ror:12 row_mask:0xf bank_mask:0x5
	v_min_u32_dpp v1, v17, v17 row_ror:4 row_mask:0xf bank_mask:0xa
	s_nop 1
	v_sub_co_u32_dpp v250, vcc, v1, v1 quad_perm:[2,3,0,1] row_mask:0xf bank_mask:0xf
	s_xor_b32 vcc_lo, vcc_lo, 0xcccccccc
	s_xor_b32 vcc_hi, vcc_hi, 0xcccccccc
	v_cndmask_b32_dpp v17, v1, v1, vcc quad_perm:[2,3,0,1] row_mask:0xf bank_mask:0xf
	s_nop 1
	v_sub_co_u32_dpp v250, vcc, v17, v17 quad_perm:[1,0,3,2] row_mask:0xf bank_mask:0xf
	s_xor_b32 vcc_lo, vcc_lo, 0xaaaaaaaa
	s_xor_b32 vcc_hi, vcc_hi, 0xaaaaaaaa
	v_cndmask_b32_dpp v1, v17, v17, vcc quad_perm:[1,0,3,2] row_mask:0xf bank_mask:0xf
	ds_swizzle_b32 v252, v1 offset:0x7c1f
	s_waitcnt lgkmcnt(0)
	v_max_u32_dpp v17, v252, v1 quad_perm:[0,1,2,3] row_mask:0x5 bank_mask:0xf
	v_min_u32_dpp v17, v252, v1 quad_perm:[0,1,2,3] row_mask:0xa bank_mask:0xf
	s_nop 1
	v_max_u32_dpp v1, v17, v17 row_ror:8 row_mask:0xf bank_mask:0x3
	v_min_u32_dpp v1, v17, v17 row_ror:8 row_mask:0xf bank_mask:0xc
	s_nop 1
	v_max_u32_dpp v17, v1, v1 row_ror:12 row_mask:0xf bank_mask:0x5
	v_min_u32_dpp v17, v1, v1 row_ror:4 row_mask:0xf bank_mask:0xa
	s_nop 1
	v_sub_co_u32_dpp v250, vcc, v17, v17 quad_perm:[2,3,0,1] row_mask:0xf bank_mask:0xf
	s_xor_b32 vcc_lo, vcc_lo, 0xcccccccc
	s_xor_b32 vcc_hi, vcc_hi, 0xcccccccc
	v_cndmask_b32_dpp v1, v17, v17, vcc quad_perm:[2,3,0,1] row_mask:0xf bank_mask:0xf
	s_nop 1
	v_sub_co_u32_dpp v250, vcc, v1, v1 quad_perm:[1,0,3,2] row_mask:0xf bank_mask:0xf
	s_xor_b32 vcc_lo, vcc_lo, 0xaaaaaaaa
	s_xor_b32 vcc_hi, vcc_hi, 0xaaaaaaaa
	v_cndmask_b32_dpp v17, v1, v1, vcc quad_perm:[1,0,3,2] row_mask:0xf bank_mask:0xf
	v_xor_b32_e32 v253, 63, v81
	v_lshlrev_b32_e32 v253, 2, v253
	ds_bpermute_b32 v252, v253, v17
	s_waitcnt lgkmcnt(0)
	v_max_u32_dpp v1, v252, v17 quad_perm:[0,1,2,3] row_mask:0x3 bank_mask:0xf
	v_min_u32_dpp v1, v252, v17 quad_perm:[0,1,2,3] row_mask:0xc bank_mask:0xf
	ds_swizzle_b32 v252, v1 offset:0x401f
	s_waitcnt lgkmcnt(0)
	v_max_u32_dpp v17, v252, v1 quad_perm:[0,1,2,3] row_mask:0x5 bank_mask:0xf
	v_min_u32_dpp v17, v252, v1 quad_perm:[0,1,2,3] row_mask:0xa bank_mask:0xf
	s_nop 1
	v_max_u32_dpp v1, v17, v17 row_ror:8 row_mask:0xf bank_mask:0x3
	v_min_u32_dpp v1, v17, v17 row_ror:8 row_mask:0xf bank_mask:0xc
	s_nop 1
	v_max_u32_dpp v17, v1, v1 row_ror:12 row_mask:0xf bank_mask:0x5
	v_min_u32_dpp v17, v1, v1 row_ror:4 row_mask:0xf bank_mask:0xa
	s_nop 1
	v_sub_co_u32_dpp v250, vcc, v17, v17 quad_perm:[2,3,0,1] row_mask:0xf bank_mask:0xf
	s_xor_b32 vcc_lo, vcc_lo, 0xcccccccc
	s_xor_b32 vcc_hi, vcc_hi, 0xcccccccc
	v_cndmask_b32_dpp v1, v17, v17, vcc quad_perm:[2,3,0,1] row_mask:0xf bank_mask:0xf
	s_nop 1
	v_sub_co_u32_dpp v250, vcc, v1, v1 quad_perm:[1,0,3,2] row_mask:0xf bank_mask:0xf
	s_xor_b32 vcc_lo, vcc_lo, 0xaaaaaaaa
	s_xor_b32 vcc_hi, vcc_hi, 0xaaaaaaaa
	v_cndmask_b32_dpp v17, v1, v1, vcc quad_perm:[1,0,3,2] row_mask:0xf bank_mask:0xf
	v_not_b32_e32 v253, v17
	v_and_b32_e32 v253, 63, v253
	v_lshlrev_b32_e32 v253, 2, v253
	ds_permute_b32 v1, v253, v81
	s_waitcnt lgkmcnt(0)
	v_lshlrev_b32_e32 v25, 3, v1
	v_lshlrev_b32_e32 v17, 7, v1
	v_and_b32_e32 v25, 0x70, v25
	v_and_or_b32 v17, v17, s43, v25
	v_cmp_gt_u32_e32 vcc, 16, v1
	s_nop 1
	v_cndmask_b32_e32 v17, 4, v17, vcc
	ds_permute_b32 v25, v17, v0
	v_mad_i64_i32 v[0:1], s[2:3], v10, s28, v[120:121]
	s_waitcnt vmcnt(23)
	v_cmp_lt_i32_e32 vcc, -1, v117
	s_waitcnt lgkmcnt(0)
	v_readlane_b32 s2, v25, 0
	s_nop 1
	v_subrev_f32_e32 v4, s2, v25
	v_mul_f32_e32 v4, 0x3fb8aa3b, v4
	v_exp_f32_e32 v6, v4
	v_mad_i64_i32 v[4:5], s[2:3], v11, s28, v[120:121]
	global_load_dwordx4 v[102:105], v[0:1], off offset:768
	global_load_dwordx4 v[98:101], v[4:5], off offset:768
	v_cndmask_b32_e64 v6, 0, v6, s[12:13]
	ds_bpermute_b32 v7, v240, v6
	v_mad_i64_i32 v[0:1], s[2:3], v12, s28, v[120:121]
	v_mad_i64_i32 v[4:5], s[2:3], v13, s28, v[120:121]
	s_waitcnt lgkmcnt(0)
	v_add_f32_e32 v7, v6, v7
	ds_bpermute_b32 v10, v241, v7
	global_load_dwordx4 v[94:97], v[0:1], off offset:768
	global_load_dwordx4 v[90:93], v[4:5], off offset:768
	v_mad_i64_i32 v[0:1], s[2:3], v14, s28, v[120:121]
	v_mad_i64_i32 v[4:5], s[2:3], v15, s28, v[120:121]
	s_waitcnt lgkmcnt(0)
	v_add_f32_e32 v7, v7, v10
	ds_bpermute_b32 v10, v242, v7
	global_load_dwordx4 v[86:89], v[0:1], off offset:768
	global_load_dwordx4 v[82:85], v[4:5], off offset:768
	v_cndmask_b32_e64 v1, v232, -1, vcc
	v_cmp_lt_i32_e32 vcc, -1, v21
	v_and_b32_e32 v0, 0xffffff80, v117
	s_waitcnt lgkmcnt(0)
	v_add_f32_e32 v7, v7, v10
	v_cndmask_b32_e64 v5, v232, -1, vcc
	s_waitcnt vmcnt(28)
	v_cmp_lt_i32_e32 vcc, -1, v31
	v_and_b32_e32 v4, 0xffffff80, v21
	v_xor_b32_e32 v1, v1, v0
	v_cndmask_b32_e64 v10, v232, -1, vcc
	v_cmp_lt_i32_e32 vcc, -1, v23
	v_xor_b32_e32 v5, v5, v4
	v_and_b32_e32 v0, 0xffffff80, v31
	v_and_b32_e32 v4, 0xffffff80, v23
	v_cndmask_b32_e64 v11, v232, -1, vcc
	v_xor_b32_e32 v0, v10, v0
	v_xor_b32_e32 v4, v11, v4
	v_pk_add_f32 v[0:1], v[4:5], v[0:1]
	ds_bpermute_b32 v9, v243, v7
	v_or_b32_e32 v4, 0x80000000, v1
	v_not_b32_e32 v5, v1
	v_cmp_gt_i32_e32 vcc, 0, v1
	s_nop 1
	v_cndmask_b32_e32 v4, v4, v5, vcc
	v_and_b32_e32 v4, 0xffffffc0, v4
	v_cndmask_b32_e64 v4, 0, v4, s[10:11]
	v_bitop3_b32 v4, v4, 63, v81 bitop3:0x36
	s_nop 0
	s_nop 1
	v_sub_co_u32_dpp v250, vcc, v4, v4 quad_perm:[1,0,3,2] row_mask:0xf bank_mask:0xf
	s_xor_b32 vcc_lo, vcc_lo, 0xaaaaaaaa
	s_xor_b32 vcc_hi, vcc_hi, 0xaaaaaaaa
	v_cndmask_b32_dpp v5, v4, v4, vcc quad_perm:[1,0,3,2] row_mask:0xf bank_mask:0xf
	s_nop 1
	v_sub_co_u32_dpp v250, vcc, v5, v5 quad_perm:[3,2,1,0] row_mask:0xf bank_mask:0xf
	s_xor_b32 vcc_lo, vcc_lo, 0xcccccccc
	s_xor_b32 vcc_hi, vcc_hi, 0xcccccccc
	v_cndmask_b32_dpp v4, v5, v5, vcc quad_perm:[3,2,1,0] row_mask:0xf bank_mask:0xf
	s_nop 1
	v_sub_co_u32_dpp v250, vcc, v4, v4 quad_perm:[1,0,3,2] row_mask:0xf bank_mask:0xf
	s_xor_b32 vcc_lo, vcc_lo, 0xaaaaaaaa
	s_xor_b32 vcc_hi, vcc_hi, 0xaaaaaaaa
	v_cndmask_b32_dpp v5, v4, v4, vcc quad_perm:[1,0,3,2] row_mask:0xf bank_mask:0xf
	s_nop 1
	v_max_u32_dpp v4, v5, v5 row_half_mirror row_mask:0xf bank_mask:0x5
	v_min_u32_dpp v4, v5, v5 row_half_mirror row_mask:0xf bank_mask:0xa
	s_nop 1
	v_sub_co_u32_dpp v250, vcc, v4, v4 quad_perm:[2,3,0,1] row_mask:0xf bank_mask:0xf
	s_xor_b32 vcc_lo, vcc_lo, 0xcccccccc
	s_xor_b32 vcc_hi, vcc_hi, 0xcccccccc
	v_cndmask_b32_dpp v5, v4, v4, vcc quad_perm:[2,3,0,1] row_mask:0xf bank_mask:0xf
	s_nop 1
	v_sub_co_u32_dpp v250, vcc, v5, v5 quad_perm:[1,0,3,2] row_mask:0xf bank_mask:0xf
	s_xor_b32 vcc_lo, vcc_lo, 0xaaaaaaaa
	s_xor_b32 vcc_hi, vcc_hi, 0xaaaaaaaa
	v_cndmask_b32_dpp v4, v5, v5, vcc quad_perm:[1,0,3,2] row_mask:0xf bank_mask:0xf
	s_nop 1
	v_max_u32_dpp v5, v4, v4 row_mirror row_mask:0xf bank_mask:0x3
	v_min_u32_dpp v5, v4, v4 row_mirror row_mask:0xf bank_mask:0xc
	s_nop 1
	v_max_u32_dpp v4, v5, v5 row_ror:12 row_mask:0xf bank_mask:0x5
	v_min_u32_dpp v4, v5, v5 row_ror:4 row_mask:0xf bank_mask:0xa
	s_nop 1
	v_sub_co_u32_dpp v250, vcc, v4, v4 quad_perm:[2,3,0,1] row_mask:0xf bank_mask:0xf
	s_xor_b32 vcc_lo, vcc_lo, 0xcccccccc
	s_xor_b32 vcc_hi, vcc_hi, 0xcccccccc
	v_cndmask_b32_dpp v5, v4, v4, vcc quad_perm:[2,3,0,1] row_mask:0xf bank_mask:0xf
	s_nop 1
	v_sub_co_u32_dpp v250, vcc, v5, v5 quad_perm:[1,0,3,2] row_mask:0xf bank_mask:0xf
	s_xor_b32 vcc_lo, vcc_lo, 0xaaaaaaaa
	s_xor_b32 vcc_hi, vcc_hi, 0xaaaaaaaa
	v_cndmask_b32_dpp v4, v5, v5, vcc quad_perm:[1,0,3,2] row_mask:0xf bank_mask:0xf
	ds_swizzle_b32 v252, v4 offset:0x7c1f
	s_waitcnt lgkmcnt(0)
	v_max_u32_dpp v5, v252, v4 quad_perm:[0,1,2,3] row_mask:0x5 bank_mask:0xf
	v_min_u32_dpp v5, v252, v4 quad_perm:[0,1,2,3] row_mask:0xa bank_mask:0xf
	s_nop 1
	v_max_u32_dpp v4, v5, v5 row_ror:8 row_mask:0xf bank_mask:0x3
	v_min_u32_dpp v4, v5, v5 row_ror:8 row_mask:0xf bank_mask:0xc
	s_nop 1
	v_max_u32_dpp v5, v4, v4 row_ror:12 row_mask:0xf bank_mask:0x5
	v_min_u32_dpp v5, v4, v4 row_ror:4 row_mask:0xf bank_mask:0xa
	s_nop 1
	v_sub_co_u32_dpp v250, vcc, v5, v5 quad_perm:[2,3,0,1] row_mask:0xf bank_mask:0xf
	s_xor_b32 vcc_lo, vcc_lo, 0xcccccccc
	s_xor_b32 vcc_hi, vcc_hi, 0xcccccccc
	v_cndmask_b32_dpp v4, v5, v5, vcc quad_perm:[2,3,0,1] row_mask:0xf bank_mask:0xf
	s_nop 1
	v_sub_co_u32_dpp v250, vcc, v4, v4 quad_perm:[1,0,3,2] row_mask:0xf bank_mask:0xf
	s_xor_b32 vcc_lo, vcc_lo, 0xaaaaaaaa
	s_xor_b32 vcc_hi, vcc_hi, 0xaaaaaaaa
	v_cndmask_b32_dpp v5, v4, v4, vcc quad_perm:[1,0,3,2] row_mask:0xf bank_mask:0xf
	v_xor_b32_e32 v253, 63, v81
	v_lshlrev_b32_e32 v253, 2, v253
	ds_bpermute_b32 v252, v253, v5
	s_waitcnt lgkmcnt(0)
	v_max_u32_dpp v4, v252, v5 quad_perm:[0,1,2,3] row_mask:0x3 bank_mask:0xf
	v_min_u32_dpp v4, v252, v5 quad_perm:[0,1,2,3] row_mask:0xc bank_mask:0xf
	ds_swizzle_b32 v252, v4 offset:0x401f
	s_waitcnt lgkmcnt(0)
	v_max_u32_dpp v5, v252, v4 quad_perm:[0,1,2,3] row_mask:0x5 bank_mask:0xf
	v_min_u32_dpp v5, v252, v4 quad_perm:[0,1,2,3] row_mask:0xa bank_mask:0xf
	s_nop 1
	v_max_u32_dpp v4, v5, v5 row_ror:8 row_mask:0xf bank_mask:0x3
	v_min_u32_dpp v4, v5, v5 row_ror:8 row_mask:0xf bank_mask:0xc
	s_nop 1
	v_max_u32_dpp v5, v4, v4 row_ror:12 row_mask:0xf bank_mask:0x5
	v_min_u32_dpp v5, v4, v4 row_ror:4 row_mask:0xf bank_mask:0xa
	s_nop 1
	v_sub_co_u32_dpp v250, vcc, v5, v5 quad_perm:[2,3,0,1] row_mask:0xf bank_mask:0xf
	s_xor_b32 vcc_lo, vcc_lo, 0xcccccccc
	s_xor_b32 vcc_hi, vcc_hi, 0xcccccccc
	v_cndmask_b32_dpp v4, v5, v5, vcc quad_perm:[2,3,0,1] row_mask:0xf bank_mask:0xf
	s_nop 1
	v_sub_co_u32_dpp v250, vcc, v4, v4 quad_perm:[1,0,3,2] row_mask:0xf bank_mask:0xf
	s_xor_b32 vcc_lo, vcc_lo, 0xaaaaaaaa
	s_xor_b32 vcc_hi, vcc_hi, 0xaaaaaaaa
	v_cndmask_b32_dpp v5, v4, v4, vcc quad_perm:[1,0,3,2] row_mask:0xf bank_mask:0xf
	v_not_b32_e32 v253, v5
	v_and_b32_e32 v253, 63, v253
	v_lshlrev_b32_e32 v253, 2, v253
	ds_permute_b32 v4, v253, v81
	s_waitcnt lgkmcnt(0)
	v_lshlrev_b32_e32 v10, 3, v4
	v_lshlrev_b32_e32 v5, 7, v4
	v_and_b32_e32 v10, 0x70, v10
	v_and_or_b32 v5, v5, s43, v10
	v_cmp_gt_u32_e32 vcc, 16, v4
	ds_permute_b32 v4, v17, v8
	s_nop 0
	v_cndmask_b32_e32 v10, 4, v5, vcc
	ds_permute_b32 v1, v10, v1
	s_waitcnt lgkmcnt(2)
	v_add_f32_e32 v5, v7, v9
	v_div_scale_f32 v7, s[2:3], v5, v5, v6
	v_rcp_f32_e32 v9, v7
	s_waitcnt lgkmcnt(0)
	v_readlane_b32 s2, v1, 0
	v_div_scale_f32 v11, vcc, v6, v5, v6
	s_nop 0
	v_subrev_f32_e32 v1, s2, v1
	v_mul_f32_e32 v1, 0x3fb8aa3b, v1
	v_exp_f32_e32 v1, v1
	v_fma_f32 v8, -v7, v9, 1.0
	v_fmac_f32_e32 v9, v8, v9
	v_mul_f32_e32 v12, v11, v9
	v_cndmask_b32_e64 v1, 0, v1, s[12:13]
	ds_bpermute_b32 v8, v240, v1
	v_fma_f32 v13, -v7, v12, v11
	v_fmac_f32_e32 v12, v13, v9
	v_fma_f32 v7, -v7, v12, v11
	v_div_fmas_f32 v7, v7, v9, v12
	s_waitcnt lgkmcnt(0)
	v_add_f32_e32 v8, v1, v8
	ds_bpermute_b32 v14, v241, v8
	v_div_fixup_f32 v5, v7, v5, v6
	v_or_b32_e32 v6, 0x80000000, v0
	v_not_b32_e32 v7, v0
	v_cmp_gt_i32_e32 vcc, 0, v0
	s_waitcnt lgkmcnt(0)
	v_add_f32_e32 v8, v8, v14
	ds_bpermute_b32 v9, v242, v8
	v_cndmask_b32_e32 v6, v6, v7, vcc
	v_and_b32_e32 v6, 0xffffffc0, v6
	v_cndmask_b32_e64 v6, 0, v6, s[10:11]
	v_bitop3_b32 v6, v6, 63, v81 bitop3:0x36
	ds_write2st64_b64 v239, v[2:3], v[4:5] offset1:1
	s_nop 1
	s_waitcnt lgkmcnt(1)
	v_add_f32_e32 v4, v8, v9
	v_sub_co_u32_dpp v250, vcc, v6, v6 quad_perm:[1,0,3,2] row_mask:0xf bank_mask:0xf
	ds_bpermute_b32 v5, v243, v4
	s_xor_b32 vcc_lo, vcc_lo, 0xaaaaaaaa
	s_xor_b32 vcc_hi, vcc_hi, 0xaaaaaaaa
	v_lshlrev_b32_e32 v2, 7, v21
	v_cndmask_b32_dpp v7, v6, v6, vcc quad_perm:[1,0,3,2] row_mask:0xf bank_mask:0xf
	s_nop 1
	v_sub_co_u32_dpp v250, vcc, v7, v7 quad_perm:[3,2,1,0] row_mask:0xf bank_mask:0xf
	v_and_b32_e32 v3, 0x7f, v117
	s_xor_b32 vcc_lo, vcc_lo, 0xcccccccc
	s_xor_b32 vcc_hi, vcc_hi, 0xcccccccc
	v_cndmask_b32_dpp v6, v7, v7, vcc quad_perm:[3,2,1,0] row_mask:0xf bank_mask:0xf
	v_and_or_b32 v2, v2, s44, v3
	s_nop 1
	v_sub_co_u32_dpp v250, vcc, v6, v6 quad_perm:[1,0,3,2] row_mask:0xf bank_mask:0xf
	s_xor_b32 vcc_lo, vcc_lo, 0xaaaaaaaa
	s_waitcnt lgkmcnt(0)
	s_xor_b32 vcc_hi, vcc_hi, 0xaaaaaaaa
	v_add_f32_e32 v3, v4, v5
	v_cndmask_b32_dpp v7, v6, v6, vcc quad_perm:[1,0,3,2] row_mask:0xf bank_mask:0xf
	s_nop 1
	v_max_u32_dpp v6, v7, v7 row_half_mirror row_mask:0xf bank_mask:0x5
	ds_permute_b32 v2, v10, v2
	v_min_u32_dpp v6, v7, v7 row_half_mirror row_mask:0xf bank_mask:0xa
	s_nop 1
	v_sub_co_u32_dpp v250, vcc, v6, v6 quad_perm:[2,3,0,1] row_mask:0xf bank_mask:0xf
	s_xor_b32 vcc_lo, vcc_lo, 0xcccccccc
	s_xor_b32 vcc_hi, vcc_hi, 0xcccccccc
	v_cndmask_b32_dpp v7, v6, v6, vcc quad_perm:[2,3,0,1] row_mask:0xf bank_mask:0xf
	s_nop 1
	v_sub_co_u32_dpp v250, vcc, v7, v7 quad_perm:[1,0,3,2] row_mask:0xf bank_mask:0xf
	s_xor_b32 vcc_lo, vcc_lo, 0xaaaaaaaa
	s_xor_b32 vcc_hi, vcc_hi, 0xaaaaaaaa
	v_cndmask_b32_dpp v6, v7, v7, vcc quad_perm:[1,0,3,2] row_mask:0xf bank_mask:0xf
	s_nop 1
	v_max_u32_dpp v7, v6, v6 row_mirror row_mask:0xf bank_mask:0x3
	v_min_u32_dpp v7, v6, v6 row_mirror row_mask:0xf bank_mask:0xc
	s_nop 1
	v_max_u32_dpp v6, v7, v7 row_ror:12 row_mask:0xf bank_mask:0x5
	v_min_u32_dpp v6, v7, v7 row_ror:4 row_mask:0xf bank_mask:0xa
	s_nop 1
	v_sub_co_u32_dpp v250, vcc, v6, v6 quad_perm:[2,3,0,1] row_mask:0xf bank_mask:0xf
	s_xor_b32 vcc_lo, vcc_lo, 0xcccccccc
	s_xor_b32 vcc_hi, vcc_hi, 0xcccccccc
	v_cndmask_b32_dpp v7, v6, v6, vcc quad_perm:[2,3,0,1] row_mask:0xf bank_mask:0xf
	s_nop 1
	v_sub_co_u32_dpp v250, vcc, v7, v7 quad_perm:[1,0,3,2] row_mask:0xf bank_mask:0xf
	s_xor_b32 vcc_lo, vcc_lo, 0xaaaaaaaa
	s_xor_b32 vcc_hi, vcc_hi, 0xaaaaaaaa
	v_cndmask_b32_dpp v6, v7, v7, vcc quad_perm:[1,0,3,2] row_mask:0xf bank_mask:0xf
	ds_swizzle_b32 v252, v6 offset:0x7c1f
	s_waitcnt lgkmcnt(0)
	v_max_u32_dpp v7, v252, v6 quad_perm:[0,1,2,3] row_mask:0x5 bank_mask:0xf
	v_min_u32_dpp v7, v252, v6 quad_perm:[0,1,2,3] row_mask:0xa bank_mask:0xf
	s_nop 1
	v_max_u32_dpp v6, v7, v7 row_ror:8 row_mask:0xf bank_mask:0x3
	v_min_u32_dpp v6, v7, v7 row_ror:8 row_mask:0xf bank_mask:0xc
	s_nop 1
	v_max_u32_dpp v7, v6, v6 row_ror:12 row_mask:0xf bank_mask:0x5
	v_min_u32_dpp v7, v6, v6 row_ror:4 row_mask:0xf bank_mask:0xa
	s_nop 1
	v_sub_co_u32_dpp v250, vcc, v7, v7 quad_perm:[2,3,0,1] row_mask:0xf bank_mask:0xf
	s_xor_b32 vcc_lo, vcc_lo, 0xcccccccc
	s_xor_b32 vcc_hi, vcc_hi, 0xcccccccc
	v_cndmask_b32_dpp v6, v7, v7, vcc quad_perm:[2,3,0,1] row_mask:0xf bank_mask:0xf
	s_nop 1
	v_sub_co_u32_dpp v250, vcc, v6, v6 quad_perm:[1,0,3,2] row_mask:0xf bank_mask:0xf
	s_xor_b32 vcc_lo, vcc_lo, 0xaaaaaaaa
	s_xor_b32 vcc_hi, vcc_hi, 0xaaaaaaaa
	v_cndmask_b32_dpp v7, v6, v6, vcc quad_perm:[1,0,3,2] row_mask:0xf bank_mask:0xf
	v_xor_b32_e32 v253, 63, v81
	v_lshlrev_b32_e32 v253, 2, v253
	ds_bpermute_b32 v252, v253, v7
	s_waitcnt lgkmcnt(0)
	v_max_u32_dpp v6, v252, v7 quad_perm:[0,1,2,3] row_mask:0x3 bank_mask:0xf
	v_min_u32_dpp v6, v252, v7 quad_perm:[0,1,2,3] row_mask:0xc bank_mask:0xf
	ds_swizzle_b32 v252, v6 offset:0x401f
	s_waitcnt lgkmcnt(0)
	v_max_u32_dpp v7, v252, v6 quad_perm:[0,1,2,3] row_mask:0x5 bank_mask:0xf
	v_min_u32_dpp v7, v252, v6 quad_perm:[0,1,2,3] row_mask:0xa bank_mask:0xf
	s_nop 1
	v_max_u32_dpp v6, v7, v7 row_ror:8 row_mask:0xf bank_mask:0x3
	v_min_u32_dpp v6, v7, v7 row_ror:8 row_mask:0xf bank_mask:0xc
	s_nop 1
	v_max_u32_dpp v7, v6, v6 row_ror:12 row_mask:0xf bank_mask:0x5
	v_min_u32_dpp v7, v6, v6 row_ror:4 row_mask:0xf bank_mask:0xa
	s_nop 1
	v_sub_co_u32_dpp v250, vcc, v7, v7 quad_perm:[2,3,0,1] row_mask:0xf bank_mask:0xf
	s_xor_b32 vcc_lo, vcc_lo, 0xcccccccc
	s_xor_b32 vcc_hi, vcc_hi, 0xcccccccc
	v_cndmask_b32_dpp v6, v7, v7, vcc quad_perm:[2,3,0,1] row_mask:0xf bank_mask:0xf
	s_nop 1
	v_sub_co_u32_dpp v250, vcc, v6, v6 quad_perm:[1,0,3,2] row_mask:0xf bank_mask:0xf
	s_xor_b32 vcc_lo, vcc_lo, 0xaaaaaaaa
	s_xor_b32 vcc_hi, vcc_hi, 0xaaaaaaaa
	v_cndmask_b32_dpp v7, v6, v6, vcc quad_perm:[1,0,3,2] row_mask:0xf bank_mask:0xf
	v_not_b32_e32 v253, v7
	v_and_b32_e32 v253, 63, v253
	v_lshlrev_b32_e32 v253, 2, v253
	ds_permute_b32 v6, v253, v81
	s_waitcnt lgkmcnt(0)
	v_lshlrev_b32_e32 v8, 3, v6
	v_lshlrev_b32_e32 v7, 7, v6
	v_and_b32_e32 v8, 0x70, v8
	v_and_or_b32 v7, v7, s43, v8
	v_cmp_gt_u32_e32 vcc, 16, v6
	v_and_b32_e32 v8, 0x7f, v31
	s_nop 0
	v_cndmask_b32_e32 v6, 4, v7, vcc
	ds_permute_b32 v0, v6, v0
	v_lshlrev_b32_e32 v7, 7, v23
	v_and_or_b32 v7, v7, s44, v8
	s_waitcnt lgkmcnt(0)
	v_readlane_b32 s2, v0, 0
	s_nop 1
	v_subrev_f32_e32 v0, s2, v0
	v_mul_f32_e32 v0, 0x3fb8aa3b, v0
	v_exp_f32_e32 v0, v0
	v_div_scale_f32 v4, s[2:3], v3, v3, v1
	v_rcp_f32_e32 v5, v4
	v_cndmask_b32_e64 v9, 0, v0, s[12:13]
	ds_bpermute_b32 v0, v240, v9
	v_fma_f32 v10, -v4, v5, 1.0
	v_fmac_f32_e32 v5, v10, v5
	v_div_scale_f32 v10, vcc, v1, v3, v1
	s_waitcnt lgkmcnt(0)
	v_add_f32_e32 v0, v9, v0
	ds_bpermute_b32 v11, v241, v0
	v_mul_f32_e32 v12, v10, v5
	v_fma_f32 v13, -v4, v12, v10
	v_fmac_f32_e32 v12, v13, v5
	v_fma_f32 v4, -v4, v12, v10
	s_waitcnt lgkmcnt(0)
	v_add_f32_e32 v0, v0, v11
	ds_bpermute_b32 v10, v242, v0
	v_div_fmas_f32 v4, v4, v5, v12
	s_waitcnt vmcnt(27)
	v_cmp_lt_i32_e32 vcc, -1, v30
	v_div_fixup_f32 v3, v4, v3, v1
	v_and_b32_e32 v4, 0xffffff80, v22
	v_cndmask_b32_e64 v1, v232, -1, vcc
	v_cmp_lt_i32_e32 vcc, -1, v22
	s_waitcnt lgkmcnt(0)
	v_add_f32_e32 v8, v0, v10
	v_and_b32_e32 v0, 0xffffff80, v30
	v_cndmask_b32_e64 v5, v232, -1, vcc
	s_waitcnt vmcnt(26)
	v_cmp_lt_i32_e32 vcc, -1, v29
	v_xor_b32_e32 v1, v1, v0
	v_xor_b32_e32 v5, v5, v4
	v_cndmask_b32_e64 v11, v232, -1, vcc
	v_cmp_lt_i32_e32 vcc, -1, v24
	v_and_b32_e32 v0, 0xffffff80, v29
	v_and_b32_e32 v4, 0xffffff80, v24
	v_cndmask_b32_e64 v12, v232, -1, vcc
	v_xor_b32_e32 v0, v11, v0
	v_xor_b32_e32 v4, v12, v4
	v_pk_add_f32 v[0:1], v[4:5], v[0:1]
	ds_bpermute_b32 v10, v243, v8
	v_or_b32_e32 v4, 0x80000000, v1
	v_not_b32_e32 v5, v1
	v_cmp_gt_i32_e32 vcc, 0, v1
	s_nop 1
	v_cndmask_b32_e32 v4, v4, v5, vcc
	v_and_b32_e32 v4, 0xffffffc0, v4
	v_cndmask_b32_e64 v4, 0, v4, s[10:11]
	v_bitop3_b32 v4, v4, 63, v81 bitop3:0x36
	s_nop 0
	s_nop 1
	v_sub_co_u32_dpp v250, vcc, v4, v4 quad_perm:[1,0,3,2] row_mask:0xf bank_mask:0xf
	s_xor_b32 vcc_lo, vcc_lo, 0xaaaaaaaa
	s_xor_b32 vcc_hi, vcc_hi, 0xaaaaaaaa
	v_cndmask_b32_dpp v5, v4, v4, vcc quad_perm:[1,0,3,2] row_mask:0xf bank_mask:0xf
	s_nop 1
	v_sub_co_u32_dpp v250, vcc, v5, v5 quad_perm:[3,2,1,0] row_mask:0xf bank_mask:0xf
	s_xor_b32 vcc_lo, vcc_lo, 0xcccccccc
	s_xor_b32 vcc_hi, vcc_hi, 0xcccccccc
	v_cndmask_b32_dpp v4, v5, v5, vcc quad_perm:[3,2,1,0] row_mask:0xf bank_mask:0xf
	s_nop 1
	v_sub_co_u32_dpp v250, vcc, v4, v4 quad_perm:[1,0,3,2] row_mask:0xf bank_mask:0xf
	s_xor_b32 vcc_lo, vcc_lo, 0xaaaaaaaa
	s_xor_b32 vcc_hi, vcc_hi, 0xaaaaaaaa
	v_cndmask_b32_dpp v5, v4, v4, vcc quad_perm:[1,0,3,2] row_mask:0xf bank_mask:0xf
	s_nop 1
	v_max_u32_dpp v4, v5, v5 row_half_mirror row_mask:0xf bank_mask:0x5
	v_min_u32_dpp v4, v5, v5 row_half_mirror row_mask:0xf bank_mask:0xa
	s_nop 1
	v_sub_co_u32_dpp v250, vcc, v4, v4 quad_perm:[2,3,0,1] row_mask:0xf bank_mask:0xf
	s_xor_b32 vcc_lo, vcc_lo, 0xcccccccc
	s_xor_b32 vcc_hi, vcc_hi, 0xcccccccc
	v_cndmask_b32_dpp v5, v4, v4, vcc quad_perm:[2,3,0,1] row_mask:0xf bank_mask:0xf
	s_nop 1
	v_sub_co_u32_dpp v250, vcc, v5, v5 quad_perm:[1,0,3,2] row_mask:0xf bank_mask:0xf
	s_xor_b32 vcc_lo, vcc_lo, 0xaaaaaaaa
	s_xor_b32 vcc_hi, vcc_hi, 0xaaaaaaaa
	v_cndmask_b32_dpp v4, v5, v5, vcc quad_perm:[1,0,3,2] row_mask:0xf bank_mask:0xf
	s_nop 1
	v_max_u32_dpp v5, v4, v4 row_mirror row_mask:0xf bank_mask:0x3
	v_min_u32_dpp v5, v4, v4 row_mirror row_mask:0xf bank_mask:0xc
	s_nop 1
	v_max_u32_dpp v4, v5, v5 row_ror:12 row_mask:0xf bank_mask:0x5
	v_min_u32_dpp v4, v5, v5 row_ror:4 row_mask:0xf bank_mask:0xa
	s_nop 1
	v_sub_co_u32_dpp v250, vcc, v4, v4 quad_perm:[2,3,0,1] row_mask:0xf bank_mask:0xf
	s_xor_b32 vcc_lo, vcc_lo, 0xcccccccc
	s_xor_b32 vcc_hi, vcc_hi, 0xcccccccc
	v_cndmask_b32_dpp v5, v4, v4, vcc quad_perm:[2,3,0,1] row_mask:0xf bank_mask:0xf
	s_nop 1
	v_sub_co_u32_dpp v250, vcc, v5, v5 quad_perm:[1,0,3,2] row_mask:0xf bank_mask:0xf
	s_xor_b32 vcc_lo, vcc_lo, 0xaaaaaaaa
	s_xor_b32 vcc_hi, vcc_hi, 0xaaaaaaaa
	v_cndmask_b32_dpp v4, v5, v5, vcc quad_perm:[1,0,3,2] row_mask:0xf bank_mask:0xf
	ds_swizzle_b32 v252, v4 offset:0x7c1f
	s_waitcnt lgkmcnt(0)
	v_max_u32_dpp v5, v252, v4 quad_perm:[0,1,2,3] row_mask:0x5 bank_mask:0xf
	v_min_u32_dpp v5, v252, v4 quad_perm:[0,1,2,3] row_mask:0xa bank_mask:0xf
	s_nop 1
	v_max_u32_dpp v4, v5, v5 row_ror:8 row_mask:0xf bank_mask:0x3
	v_min_u32_dpp v4, v5, v5 row_ror:8 row_mask:0xf bank_mask:0xc
	s_nop 1
	v_max_u32_dpp v5, v4, v4 row_ror:12 row_mask:0xf bank_mask:0x5
	v_min_u32_dpp v5, v4, v4 row_ror:4 row_mask:0xf bank_mask:0xa
	s_nop 1
	v_sub_co_u32_dpp v250, vcc, v5, v5 quad_perm:[2,3,0,1] row_mask:0xf bank_mask:0xf
	s_xor_b32 vcc_lo, vcc_lo, 0xcccccccc
	s_xor_b32 vcc_hi, vcc_hi, 0xcccccccc
	v_cndmask_b32_dpp v4, v5, v5, vcc quad_perm:[2,3,0,1] row_mask:0xf bank_mask:0xf
	s_nop 1
	v_sub_co_u32_dpp v250, vcc, v4, v4 quad_perm:[1,0,3,2] row_mask:0xf bank_mask:0xf
	s_xor_b32 vcc_lo, vcc_lo, 0xaaaaaaaa
	s_xor_b32 vcc_hi, vcc_hi, 0xaaaaaaaa
	v_cndmask_b32_dpp v5, v4, v4, vcc quad_perm:[1,0,3,2] row_mask:0xf bank_mask:0xf
	v_xor_b32_e32 v253, 63, v81
	v_lshlrev_b32_e32 v253, 2, v253
	ds_bpermute_b32 v252, v253, v5
	s_waitcnt lgkmcnt(0)
	v_max_u32_dpp v4, v252, v5 quad_perm:[0,1,2,3] row_mask:0x3 bank_mask:0xf
	v_min_u32_dpp v4, v252, v5 quad_perm:[0,1,2,3] row_mask:0xc bank_mask:0xf
	ds_swizzle_b32 v252, v4 offset:0x401f
	s_waitcnt lgkmcnt(0)
	v_max_u32_dpp v5, v252, v4 quad_perm:[0,1,2,3] row_mask:0x5 bank_mask:0xf
	v_min_u32_dpp v5, v252, v4 quad_perm:[0,1,2,3] row_mask:0xa bank_mask:0xf
	s_nop 1
	v_max_u32_dpp v4, v5, v5 row_ror:8 row_mask:0xf bank_mask:0x3
	v_min_u32_dpp v4, v5, v5 row_ror:8 row_mask:0xf bank_mask:0xc
	s_nop 1
	v_max_u32_dpp v5, v4, v4 row_ror:12 row_mask:0xf bank_mask:0x5
	v_min_u32_dpp v5, v4, v4 row_ror:4 row_mask:0xf bank_mask:0xa
	s_nop 1
	v_sub_co_u32_dpp v250, vcc, v5, v5 quad_perm:[2,3,0,1] row_mask:0xf bank_mask:0xf
	s_xor_b32 vcc_lo, vcc_lo, 0xcccccccc
	s_xor_b32 vcc_hi, vcc_hi, 0xcccccccc
	v_cndmask_b32_dpp v4, v5, v5, vcc quad_perm:[2,3,0,1] row_mask:0xf bank_mask:0xf
	s_nop 1
	v_sub_co_u32_dpp v250, vcc, v4, v4 quad_perm:[1,0,3,2] row_mask:0xf bank_mask:0xf
	s_xor_b32 vcc_lo, vcc_lo, 0xaaaaaaaa
	s_xor_b32 vcc_hi, vcc_hi, 0xaaaaaaaa
	v_cndmask_b32_dpp v5, v4, v4, vcc quad_perm:[1,0,3,2] row_mask:0xf bank_mask:0xf
	v_not_b32_e32 v253, v5
	v_and_b32_e32 v253, 63, v253
	v_lshlrev_b32_e32 v253, 2, v253
	ds_permute_b32 v4, v253, v81
	s_waitcnt lgkmcnt(0)
	v_lshlrev_b32_e32 v11, 3, v4
	v_lshlrev_b32_e32 v5, 7, v4
	v_and_b32_e32 v11, 0x70, v11
	v_and_or_b32 v5, v5, s43, v11
	v_cmp_gt_u32_e32 vcc, 16, v4
	ds_permute_b32 v4, v6, v7
	s_nop 0
	v_cndmask_b32_e32 v11, 4, v5, vcc
	ds_permute_b32 v1, v11, v1
	s_waitcnt lgkmcnt(2)
	v_add_f32_e32 v5, v8, v10
	v_div_scale_f32 v8, s[2:3], v5, v5, v9
	v_rcp_f32_e32 v10, v8
	s_waitcnt lgkmcnt(0)
	v_readlane_b32 s2, v1, 0
	v_div_scale_f32 v7, vcc, v9, v5, v9
	s_nop 0
	v_subrev_f32_e32 v1, s2, v1
	v_mul_f32_e32 v1, 0x3fb8aa3b, v1
	v_exp_f32_e32 v1, v1
	v_fma_f32 v6, -v8, v10, 1.0
	v_fmac_f32_e32 v10, v6, v10
	v_mul_f32_e32 v12, v7, v10
	v_cndmask_b32_e64 v1, 0, v1, s[12:13]
	ds_bpermute_b32 v6, v240, v1
	v_fma_f32 v13, -v8, v12, v7
	v_fmac_f32_e32 v12, v13, v10
	v_fma_f32 v7, -v8, v12, v7
	v_div_fmas_f32 v7, v7, v10, v12
	s_waitcnt lgkmcnt(0)
	v_add_f32_e32 v6, v1, v6
	ds_bpermute_b32 v14, v241, v6
	v_div_fixup_f32 v5, v7, v5, v9
	ds_write2st64_b64 v239, v[2:3], v[4:5] offset0:2 offset1:3
	v_not_b32_e32 v7, v0
	v_cmp_gt_i32_e32 vcc, 0, v0
	s_waitcnt lgkmcnt(1)
	v_add_f32_e32 v6, v6, v14
	ds_bpermute_b32 v8, v242, v6
	v_lshlrev_b32_e32 v2, 7, v22
	v_and_b32_e32 v3, 0x7f, v30
	v_and_or_b32 v2, v2, s44, v3
	v_lshlrev_b32_e32 v3, 7, v24
	s_waitcnt lgkmcnt(0)
	v_add_f32_e32 v4, v6, v8
	v_or_b32_e32 v6, 0x80000000, v0
	v_cndmask_b32_e32 v6, v6, v7, vcc
	v_and_b32_e32 v6, 0xffffffc0, v6
	v_cndmask_b32_e64 v6, 0, v6, s[10:11]
	v_bitop3_b32 v6, v6, 63, v81 bitop3:0x36
	ds_bpermute_b32 v5, v243, v4
	s_nop 1
	s_waitcnt lgkmcnt(0)
	v_sub_co_u32_dpp v250, vcc, v6, v6 quad_perm:[1,0,3,2] row_mask:0xf bank_mask:0xf
	v_add_f32_e32 v4, v4, v5
	s_xor_b32 vcc_lo, vcc_lo, 0xaaaaaaaa
	s_xor_b32 vcc_hi, vcc_hi, 0xaaaaaaaa
	v_cndmask_b32_dpp v7, v6, v6, vcc quad_perm:[1,0,3,2] row_mask:0xf bank_mask:0xf
	s_nop 1
	v_sub_co_u32_dpp v250, vcc, v7, v7 quad_perm:[3,2,1,0] row_mask:0xf bank_mask:0xf
	s_xor_b32 vcc_lo, vcc_lo, 0xcccccccc
	s_xor_b32 vcc_hi, vcc_hi, 0xcccccccc
	v_cndmask_b32_dpp v6, v7, v7, vcc quad_perm:[3,2,1,0] row_mask:0xf bank_mask:0xf
	s_nop 1
	v_sub_co_u32_dpp v250, vcc, v6, v6 quad_perm:[1,0,3,2] row_mask:0xf bank_mask:0xf
	s_xor_b32 vcc_lo, vcc_lo, 0xaaaaaaaa
	s_xor_b32 vcc_hi, vcc_hi, 0xaaaaaaaa
	v_cndmask_b32_dpp v7, v6, v6, vcc quad_perm:[1,0,3,2] row_mask:0xf bank_mask:0xf
	s_nop 1
	v_max_u32_dpp v6, v7, v7 row_half_mirror row_mask:0xf bank_mask:0x5
	v_min_u32_dpp v6, v7, v7 row_half_mirror row_mask:0xf bank_mask:0xa
	s_nop 1
	v_sub_co_u32_dpp v250, vcc, v6, v6 quad_perm:[2,3,0,1] row_mask:0xf bank_mask:0xf
	s_xor_b32 vcc_lo, vcc_lo, 0xcccccccc
	s_xor_b32 vcc_hi, vcc_hi, 0xcccccccc
	v_cndmask_b32_dpp v7, v6, v6, vcc quad_perm:[2,3,0,1] row_mask:0xf bank_mask:0xf
	s_nop 1
	v_sub_co_u32_dpp v250, vcc, v7, v7 quad_perm:[1,0,3,2] row_mask:0xf bank_mask:0xf
	s_xor_b32 vcc_lo, vcc_lo, 0xaaaaaaaa
	s_xor_b32 vcc_hi, vcc_hi, 0xaaaaaaaa
	v_cndmask_b32_dpp v6, v7, v7, vcc quad_perm:[1,0,3,2] row_mask:0xf bank_mask:0xf
	s_nop 1
	v_max_u32_dpp v7, v6, v6 row_mirror row_mask:0xf bank_mask:0x3
	v_min_u32_dpp v7, v6, v6 row_mirror row_mask:0xf bank_mask:0xc
	s_nop 1
	v_max_u32_dpp v6, v7, v7 row_ror:12 row_mask:0xf bank_mask:0x5
	v_min_u32_dpp v6, v7, v7 row_ror:4 row_mask:0xf bank_mask:0xa
	s_nop 1
	v_sub_co_u32_dpp v250, vcc, v6, v6 quad_perm:[2,3,0,1] row_mask:0xf bank_mask:0xf
	s_xor_b32 vcc_lo, vcc_lo, 0xcccccccc
	s_xor_b32 vcc_hi, vcc_hi, 0xcccccccc
	v_cndmask_b32_dpp v7, v6, v6, vcc quad_perm:[2,3,0,1] row_mask:0xf bank_mask:0xf
	s_nop 1
	v_sub_co_u32_dpp v250, vcc, v7, v7 quad_perm:[1,0,3,2] row_mask:0xf bank_mask:0xf
	s_xor_b32 vcc_lo, vcc_lo, 0xaaaaaaaa
	s_xor_b32 vcc_hi, vcc_hi, 0xaaaaaaaa
	v_cndmask_b32_dpp v6, v7, v7, vcc quad_perm:[1,0,3,2] row_mask:0xf bank_mask:0xf
	ds_swizzle_b32 v252, v6 offset:0x7c1f
	s_waitcnt lgkmcnt(0)
	v_max_u32_dpp v7, v252, v6 quad_perm:[0,1,2,3] row_mask:0x5 bank_mask:0xf
	v_min_u32_dpp v7, v252, v6 quad_perm:[0,1,2,3] row_mask:0xa bank_mask:0xf
	s_nop 1
	v_max_u32_dpp v6, v7, v7 row_ror:8 row_mask:0xf bank_mask:0x3
	v_min_u32_dpp v6, v7, v7 row_ror:8 row_mask:0xf bank_mask:0xc
	s_nop 1
	v_max_u32_dpp v7, v6, v6 row_ror:12 row_mask:0xf bank_mask:0x5
	v_min_u32_dpp v7, v6, v6 row_ror:4 row_mask:0xf bank_mask:0xa
	s_nop 1
	v_sub_co_u32_dpp v250, vcc, v7, v7 quad_perm:[2,3,0,1] row_mask:0xf bank_mask:0xf
	s_xor_b32 vcc_lo, vcc_lo, 0xcccccccc
	s_xor_b32 vcc_hi, vcc_hi, 0xcccccccc
	v_cndmask_b32_dpp v6, v7, v7, vcc quad_perm:[2,3,0,1] row_mask:0xf bank_mask:0xf
	s_nop 1
	v_sub_co_u32_dpp v250, vcc, v6, v6 quad_perm:[1,0,3,2] row_mask:0xf bank_mask:0xf
	s_xor_b32 vcc_lo, vcc_lo, 0xaaaaaaaa
	s_xor_b32 vcc_hi, vcc_hi, 0xaaaaaaaa
	v_cndmask_b32_dpp v7, v6, v6, vcc quad_perm:[1,0,3,2] row_mask:0xf bank_mask:0xf
	v_xor_b32_e32 v253, 63, v81
	v_lshlrev_b32_e32 v253, 2, v253
	ds_bpermute_b32 v252, v253, v7
	s_waitcnt lgkmcnt(0)
	v_max_u32_dpp v6, v252, v7 quad_perm:[0,1,2,3] row_mask:0x3 bank_mask:0xf
	v_min_u32_dpp v6, v252, v7 quad_perm:[0,1,2,3] row_mask:0xc bank_mask:0xf
	ds_swizzle_b32 v252, v6 offset:0x401f
	s_waitcnt lgkmcnt(0)
	v_max_u32_dpp v7, v252, v6 quad_perm:[0,1,2,3] row_mask:0x5 bank_mask:0xf
	v_min_u32_dpp v7, v252, v6 quad_perm:[0,1,2,3] row_mask:0xa bank_mask:0xf
	s_nop 1
	v_max_u32_dpp v6, v7, v7 row_ror:8 row_mask:0xf bank_mask:0x3
	v_min_u32_dpp v6, v7, v7 row_ror:8 row_mask:0xf bank_mask:0xc
	s_nop 1
	v_max_u32_dpp v7, v6, v6 row_ror:12 row_mask:0xf bank_mask:0x5
	v_min_u32_dpp v7, v6, v6 row_ror:4 row_mask:0xf bank_mask:0xa
	s_nop 1
	v_sub_co_u32_dpp v250, vcc, v7, v7 quad_perm:[2,3,0,1] row_mask:0xf bank_mask:0xf
	s_xor_b32 vcc_lo, vcc_lo, 0xcccccccc
	s_xor_b32 vcc_hi, vcc_hi, 0xcccccccc
	v_cndmask_b32_dpp v6, v7, v7, vcc quad_perm:[2,3,0,1] row_mask:0xf bank_mask:0xf
	s_nop 1
	v_sub_co_u32_dpp v250, vcc, v6, v6 quad_perm:[1,0,3,2] row_mask:0xf bank_mask:0xf
	s_xor_b32 vcc_lo, vcc_lo, 0xaaaaaaaa
	s_xor_b32 vcc_hi, vcc_hi, 0xaaaaaaaa
	v_cndmask_b32_dpp v7, v6, v6, vcc quad_perm:[1,0,3,2] row_mask:0xf bank_mask:0xf
	v_not_b32_e32 v253, v7
	v_and_b32_e32 v253, 63, v253
	v_lshlrev_b32_e32 v253, 2, v253
	ds_permute_b32 v6, v253, v81
	s_waitcnt lgkmcnt(0)
	v_lshlrev_b32_e32 v8, 3, v6
	v_lshlrev_b32_e32 v7, 7, v6
	v_and_b32_e32 v8, 0x70, v8
	v_and_or_b32 v7, v7, s43, v8
	v_cmp_gt_u32_e32 vcc, 16, v6
	s_nop 1
	v_cndmask_b32_e32 v6, 4, v7, vcc
	ds_permute_b32 v0, v6, v0
	v_and_b32_e32 v7, 0x7f, v29
	v_and_or_b32 v7, v3, s44, v7
	s_waitcnt lgkmcnt(0)
	v_readlane_b32 s2, v0, 0
	s_nop 1
	v_subrev_f32_e32 v0, s2, v0
	v_mul_f32_e32 v0, 0x3fb8aa3b, v0
	v_exp_f32_e32 v5, v0
	ds_permute_b32 v0, v11, v2
	v_div_scale_f32 v8, s[2:3], v4, v4, v1
	v_cndmask_b32_e64 v10, 0, v5, s[12:13]
	ds_bpermute_b32 v2, v240, v10
	v_rcp_f32_e32 v9, v8
	s_waitcnt lgkmcnt(0)
	v_add_f32_e32 v2, v10, v2
	ds_bpermute_b32 v11, v241, v2
	v_fma_f32 v5, -v8, v9, 1.0
	v_fmac_f32_e32 v9, v5, v9
	v_div_scale_f32 v5, vcc, v1, v4, v1
	v_mul_f32_e32 v12, v5, v9
	v_fma_f32 v13, -v8, v12, v5
	v_fmac_f32_e32 v12, v13, v9
	s_waitcnt lgkmcnt(0)
	v_add_f32_e32 v2, v2, v11
	v_fma_f32 v5, -v8, v12, v5
	ds_bpermute_b32 v8, v242, v2
	v_div_fmas_f32 v5, v5, v9, v12
	s_waitcnt vmcnt(25)
	v_cmp_lt_i32_e32 vcc, -1, v19
	v_div_fixup_f32 v1, v5, v4, v1
	v_and_b32_e32 v4, 0xffffff80, v20
	v_cndmask_b32_e64 v3, v232, -1, vcc
	v_cmp_lt_i32_e32 vcc, -1, v20
	s_waitcnt lgkmcnt(0)
	v_add_f32_e32 v8, v2, v8
	v_and_b32_e32 v2, 0xffffff80, v19
	v_cndmask_b32_e64 v5, v232, -1, vcc
	s_waitcnt vmcnt(24)
	v_cmp_lt_i32_e32 vcc, -1, v16
	v_xor_b32_e32 v3, v3, v2
	v_xor_b32_e32 v5, v5, v4
	v_cndmask_b32_e64 v11, v232, -1, vcc
	v_cmp_lt_i32_e32 vcc, -1, v18
	v_and_b32_e32 v2, 0xffffff80, v16
	v_and_b32_e32 v4, 0xffffff80, v18
	v_cndmask_b32_e64 v12, v232, -1, vcc
	v_xor_b32_e32 v2, v11, v2
	v_xor_b32_e32 v4, v12, v4
	v_pk_add_f32 v[2:3], v[4:5], v[2:3]
	ds_bpermute_b32 v9, v243, v8
	v_or_b32_e32 v4, 0x80000000, v3
	v_not_b32_e32 v5, v3
	v_cmp_gt_i32_e32 vcc, 0, v3
	s_nop 1
	v_cndmask_b32_e32 v4, v4, v5, vcc
	v_and_b32_e32 v4, 0xffffffc0, v4
	v_cndmask_b32_e64 v4, 0, v4, s[10:11]
	v_bitop3_b32 v4, v4, 63, v81 bitop3:0x36
	s_nop 0
	s_nop 1
	v_sub_co_u32_dpp v250, vcc, v4, v4 quad_perm:[1,0,3,2] row_mask:0xf bank_mask:0xf
	s_xor_b32 vcc_lo, vcc_lo, 0xaaaaaaaa
	s_xor_b32 vcc_hi, vcc_hi, 0xaaaaaaaa
	v_cndmask_b32_dpp v5, v4, v4, vcc quad_perm:[1,0,3,2] row_mask:0xf bank_mask:0xf
	s_nop 1
	v_sub_co_u32_dpp v250, vcc, v5, v5 quad_perm:[3,2,1,0] row_mask:0xf bank_mask:0xf
	s_xor_b32 vcc_lo, vcc_lo, 0xcccccccc
	s_xor_b32 vcc_hi, vcc_hi, 0xcccccccc
	v_cndmask_b32_dpp v4, v5, v5, vcc quad_perm:[3,2,1,0] row_mask:0xf bank_mask:0xf
	s_nop 1
	v_sub_co_u32_dpp v250, vcc, v4, v4 quad_perm:[1,0,3,2] row_mask:0xf bank_mask:0xf
	s_xor_b32 vcc_lo, vcc_lo, 0xaaaaaaaa
	s_xor_b32 vcc_hi, vcc_hi, 0xaaaaaaaa
	v_cndmask_b32_dpp v5, v4, v4, vcc quad_perm:[1,0,3,2] row_mask:0xf bank_mask:0xf
	s_nop 1
	v_max_u32_dpp v4, v5, v5 row_half_mirror row_mask:0xf bank_mask:0x5
	v_min_u32_dpp v4, v5, v5 row_half_mirror row_mask:0xf bank_mask:0xa
	s_nop 1
	v_sub_co_u32_dpp v250, vcc, v4, v4 quad_perm:[2,3,0,1] row_mask:0xf bank_mask:0xf
	s_xor_b32 vcc_lo, vcc_lo, 0xcccccccc
	s_xor_b32 vcc_hi, vcc_hi, 0xcccccccc
	v_cndmask_b32_dpp v5, v4, v4, vcc quad_perm:[2,3,0,1] row_mask:0xf bank_mask:0xf
	s_nop 1
	v_sub_co_u32_dpp v250, vcc, v5, v5 quad_perm:[1,0,3,2] row_mask:0xf bank_mask:0xf
	s_xor_b32 vcc_lo, vcc_lo, 0xaaaaaaaa
	s_xor_b32 vcc_hi, vcc_hi, 0xaaaaaaaa
	v_cndmask_b32_dpp v4, v5, v5, vcc quad_perm:[1,0,3,2] row_mask:0xf bank_mask:0xf
	s_nop 1
	v_max_u32_dpp v5, v4, v4 row_mirror row_mask:0xf bank_mask:0x3
	v_min_u32_dpp v5, v4, v4 row_mirror row_mask:0xf bank_mask:0xc
	s_nop 1
	v_max_u32_dpp v4, v5, v5 row_ror:12 row_mask:0xf bank_mask:0x5
	v_min_u32_dpp v4, v5, v5 row_ror:4 row_mask:0xf bank_mask:0xa
	s_nop 1
	v_sub_co_u32_dpp v250, vcc, v4, v4 quad_perm:[2,3,0,1] row_mask:0xf bank_mask:0xf
	s_xor_b32 vcc_lo, vcc_lo, 0xcccccccc
	s_xor_b32 vcc_hi, vcc_hi, 0xcccccccc
	v_cndmask_b32_dpp v5, v4, v4, vcc quad_perm:[2,3,0,1] row_mask:0xf bank_mask:0xf
	s_nop 1
	v_sub_co_u32_dpp v250, vcc, v5, v5 quad_perm:[1,0,3,2] row_mask:0xf bank_mask:0xf
	s_xor_b32 vcc_lo, vcc_lo, 0xaaaaaaaa
	s_xor_b32 vcc_hi, vcc_hi, 0xaaaaaaaa
	v_cndmask_b32_dpp v4, v5, v5, vcc quad_perm:[1,0,3,2] row_mask:0xf bank_mask:0xf
	ds_swizzle_b32 v252, v4 offset:0x7c1f
	s_waitcnt lgkmcnt(0)
	v_max_u32_dpp v5, v252, v4 quad_perm:[0,1,2,3] row_mask:0x5 bank_mask:0xf
	v_min_u32_dpp v5, v252, v4 quad_perm:[0,1,2,3] row_mask:0xa bank_mask:0xf
	s_nop 1
	v_max_u32_dpp v4, v5, v5 row_ror:8 row_mask:0xf bank_mask:0x3
	v_min_u32_dpp v4, v5, v5 row_ror:8 row_mask:0xf bank_mask:0xc
	s_nop 1
	v_max_u32_dpp v5, v4, v4 row_ror:12 row_mask:0xf bank_mask:0x5
	v_min_u32_dpp v5, v4, v4 row_ror:4 row_mask:0xf bank_mask:0xa
	s_nop 1
	v_sub_co_u32_dpp v250, vcc, v5, v5 quad_perm:[2,3,0,1] row_mask:0xf bank_mask:0xf
	s_xor_b32 vcc_lo, vcc_lo, 0xcccccccc
	s_xor_b32 vcc_hi, vcc_hi, 0xcccccccc
	v_cndmask_b32_dpp v4, v5, v5, vcc quad_perm:[2,3,0,1] row_mask:0xf bank_mask:0xf
	s_nop 1
	v_sub_co_u32_dpp v250, vcc, v4, v4 quad_perm:[1,0,3,2] row_mask:0xf bank_mask:0xf
	s_xor_b32 vcc_lo, vcc_lo, 0xaaaaaaaa
	s_xor_b32 vcc_hi, vcc_hi, 0xaaaaaaaa
	v_cndmask_b32_dpp v5, v4, v4, vcc quad_perm:[1,0,3,2] row_mask:0xf bank_mask:0xf
	v_xor_b32_e32 v253, 63, v81
	v_lshlrev_b32_e32 v253, 2, v253
	ds_bpermute_b32 v252, v253, v5
	s_waitcnt lgkmcnt(0)
	v_max_u32_dpp v4, v252, v5 quad_perm:[0,1,2,3] row_mask:0x3 bank_mask:0xf
	v_min_u32_dpp v4, v252, v5 quad_perm:[0,1,2,3] row_mask:0xc bank_mask:0xf
	ds_swizzle_b32 v252, v4 offset:0x401f
	s_waitcnt lgkmcnt(0)
	v_max_u32_dpp v5, v252, v4 quad_perm:[0,1,2,3] row_mask:0x5 bank_mask:0xf
	v_min_u32_dpp v5, v252, v4 quad_perm:[0,1,2,3] row_mask:0xa bank_mask:0xf
	s_nop 1
	v_max_u32_dpp v4, v5, v5 row_ror:8 row_mask:0xf bank_mask:0x3
	v_min_u32_dpp v4, v5, v5 row_ror:8 row_mask:0xf bank_mask:0xc
	s_nop 1
	v_max_u32_dpp v5, v4, v4 row_ror:12 row_mask:0xf bank_mask:0x5
	v_min_u32_dpp v5, v4, v4 row_ror:4 row_mask:0xf bank_mask:0xa
	s_nop 1
	v_sub_co_u32_dpp v250, vcc, v5, v5 quad_perm:[2,3,0,1] row_mask:0xf bank_mask:0xf
	s_xor_b32 vcc_lo, vcc_lo, 0xcccccccc
	s_xor_b32 vcc_hi, vcc_hi, 0xcccccccc
	v_cndmask_b32_dpp v4, v5, v5, vcc quad_perm:[2,3,0,1] row_mask:0xf bank_mask:0xf
	s_nop 1
	v_sub_co_u32_dpp v250, vcc, v4, v4 quad_perm:[1,0,3,2] row_mask:0xf bank_mask:0xf
	s_xor_b32 vcc_lo, vcc_lo, 0xaaaaaaaa
	s_xor_b32 vcc_hi, vcc_hi, 0xaaaaaaaa
	v_cndmask_b32_dpp v5, v4, v4, vcc quad_perm:[1,0,3,2] row_mask:0xf bank_mask:0xf
	v_not_b32_e32 v253, v5
	v_and_b32_e32 v253, 63, v253
	v_lshlrev_b32_e32 v253, 2, v253
	ds_permute_b32 v4, v253, v81
	s_waitcnt lgkmcnt(0)
	v_lshlrev_b32_e32 v11, 3, v4
	v_lshlrev_b32_e32 v5, 7, v4
	v_and_b32_e32 v11, 0x70, v11
	v_and_or_b32 v5, v5, s43, v11
	v_cmp_gt_u32_e32 vcc, 16, v4
	ds_permute_b32 v4, v6, v7
	s_nop 0
	v_cndmask_b32_e32 v11, 4, v5, vcc
	s_waitcnt lgkmcnt(1)
	v_add_f32_e32 v5, v8, v9
	v_div_scale_f32 v8, s[2:3], v5, v5, v10
	v_rcp_f32_e32 v9, v8
	v_div_scale_f32 v7, vcc, v10, v5, v10
	ds_permute_b32 v3, v11, v3
	v_fma_f32 v6, -v8, v9, 1.0
	v_fmac_f32_e32 v9, v6, v9
	v_mul_f32_e32 v12, v7, v9
	v_fma_f32 v13, -v8, v12, v7
	v_fmac_f32_e32 v12, v13, v9
	v_fma_f32 v7, -v8, v12, v7
	v_div_fmas_f32 v7, v7, v9, v12
	v_or_b32_e32 v8, 0x80000000, v2
	v_not_b32_e32 v9, v2
	v_cmp_gt_i32_e32 vcc, 0, v2
	s_waitcnt lgkmcnt(0)
	v_readlane_b32 s2, v3, 0
	v_div_fixup_f32 v5, v7, v5, v10
	v_cndmask_b32_e32 v8, v8, v9, vcc
	v_and_b32_e32 v8, 0xffffffc0, v8
	v_cndmask_b32_e64 v8, 0, v8, s[10:11]
	v_bitop3_b32 v8, v8, 63, v81 bitop3:0x36
	v_subrev_f32_e32 v3, s2, v3
	s_nop 1
	v_mul_f32_e32 v3, 0x3fb8aa3b, v3
	v_exp_f32_e32 v3, v3
	v_sub_co_u32_dpp v250, vcc, v8, v8 quad_perm:[1,0,3,2] row_mask:0xf bank_mask:0xf
	s_xor_b32 vcc_lo, vcc_lo, 0xaaaaaaaa
	s_xor_b32 vcc_hi, vcc_hi, 0xaaaaaaaa
	ds_write2st64_b64 v239, v[0:1], v[4:5] offset0:4 offset1:5
	v_cndmask_b32_dpp v9, v8, v8, vcc quad_perm:[1,0,3,2] row_mask:0xf bank_mask:0xf
	s_nop 1
	v_sub_co_u32_dpp v250, vcc, v9, v9 quad_perm:[3,2,1,0] row_mask:0xf bank_mask:0xf
	v_cndmask_b32_e64 v3, 0, v3, s[12:13]
	s_xor_b32 vcc_lo, vcc_lo, 0xcccccccc
	s_xor_b32 vcc_hi, vcc_hi, 0xcccccccc
	v_cndmask_b32_dpp v8, v9, v9, vcc quad_perm:[3,2,1,0] row_mask:0xf bank_mask:0xf
	ds_bpermute_b32 v6, v240, v3
	s_nop 1
	v_sub_co_u32_dpp v250, vcc, v8, v8 quad_perm:[1,0,3,2] row_mask:0xf bank_mask:0xf
	s_xor_b32 vcc_lo, vcc_lo, 0xaaaaaaaa
	v_lshlrev_b32_e32 v0, 7, v20
	s_xor_b32 vcc_hi, vcc_hi, 0xaaaaaaaa
	v_cndmask_b32_dpp v9, v8, v8, vcc quad_perm:[1,0,3,2] row_mask:0xf bank_mask:0xf
	s_nop 1
	s_waitcnt lgkmcnt(0)
	v_add_f32_e32 v6, v3, v6
	v_max_u32_dpp v8, v9, v9 row_half_mirror row_mask:0xf bank_mask:0x5
	v_min_u32_dpp v8, v9, v9 row_half_mirror row_mask:0xf bank_mask:0xa
	s_nop 1
	ds_bpermute_b32 v13, v241, v6
	v_sub_co_u32_dpp v250, vcc, v8, v8 quad_perm:[2,3,0,1] row_mask:0xf bank_mask:0xf
	s_xor_b32 vcc_lo, vcc_lo, 0xcccccccc
	s_xor_b32 vcc_hi, vcc_hi, 0xcccccccc
	s_waitcnt lgkmcnt(0)
	v_cndmask_b32_dpp v9, v8, v8, vcc quad_perm:[2,3,0,1] row_mask:0xf bank_mask:0xf
	v_add_f32_e32 v6, v6, v13
	s_nop 1
	v_sub_co_u32_dpp v250, vcc, v9, v9 quad_perm:[1,0,3,2] row_mask:0xf bank_mask:0xf
	s_xor_b32 vcc_lo, vcc_lo, 0xaaaaaaaa
	ds_bpermute_b32 v7, v242, v6
	s_xor_b32 vcc_hi, vcc_hi, 0xaaaaaaaa
	v_cndmask_b32_dpp v8, v9, v9, vcc quad_perm:[1,0,3,2] row_mask:0xf bank_mask:0xf
	s_nop 1
	v_and_b32_e32 v1, 0x7f, v19
	v_max_u32_dpp v9, v8, v8 row_mirror row_mask:0xf bank_mask:0x3
	v_min_u32_dpp v9, v8, v8 row_mirror row_mask:0xf bank_mask:0xc
	s_nop 1
	s_waitcnt lgkmcnt(0)
	v_max_u32_dpp v8, v9, v9 row_ror:12 row_mask:0xf bank_mask:0x5
	v_add_f32_e32 v4, v6, v7
	v_min_u32_dpp v8, v9, v9 row_ror:4 row_mask:0xf bank_mask:0xa
	s_nop 1
	v_sub_co_u32_dpp v250, vcc, v8, v8 quad_perm:[2,3,0,1] row_mask:0xf bank_mask:0xf
	v_and_or_b32 v0, v0, s44, v1
	s_xor_b32 vcc_lo, vcc_lo, 0xcccccccc
	s_xor_b32 vcc_hi, vcc_hi, 0xcccccccc
	v_cndmask_b32_dpp v9, v8, v8, vcc quad_perm:[2,3,0,1] row_mask:0xf bank_mask:0xf
	ds_bpermute_b32 v5, v243, v4
	s_nop 1
	v_sub_co_u32_dpp v250, vcc, v9, v9 quad_perm:[1,0,3,2] row_mask:0xf bank_mask:0xf
	s_xor_b32 vcc_lo, vcc_lo, 0xaaaaaaaa
	ds_permute_b32 v0, v11, v0
	s_xor_b32 vcc_hi, vcc_hi, 0xaaaaaaaa
	v_cndmask_b32_dpp v8, v9, v9, vcc quad_perm:[1,0,3,2] row_mask:0xf bank_mask:0xf
	v_lshlrev_b32_e32 v6, 7, v18
	ds_swizzle_b32 v252, v8 offset:0x7c1f
	s_waitcnt lgkmcnt(0)
	v_max_u32_dpp v9, v252, v8 quad_perm:[0,1,2,3] row_mask:0x5 bank_mask:0xf
	v_min_u32_dpp v9, v252, v8 quad_perm:[0,1,2,3] row_mask:0xa bank_mask:0xf
	s_nop 1
	v_max_u32_dpp v8, v9, v9 row_ror:8 row_mask:0xf bank_mask:0x3
	v_min_u32_dpp v8, v9, v9 row_ror:8 row_mask:0xf bank_mask:0xc
	s_nop 1
	v_max_u32_dpp v9, v8, v8 row_ror:12 row_mask:0xf bank_mask:0x5
	v_min_u32_dpp v9, v8, v8 row_ror:4 row_mask:0xf bank_mask:0xa
	s_nop 1
	v_sub_co_u32_dpp v250, vcc, v9, v9 quad_perm:[2,3,0,1] row_mask:0xf bank_mask:0xf
	s_xor_b32 vcc_lo, vcc_lo, 0xcccccccc
	s_xor_b32 vcc_hi, vcc_hi, 0xcccccccc
	v_cndmask_b32_dpp v8, v9, v9, vcc quad_perm:[2,3,0,1] row_mask:0xf bank_mask:0xf
	s_nop 1
	v_sub_co_u32_dpp v250, vcc, v8, v8 quad_perm:[1,0,3,2] row_mask:0xf bank_mask:0xf
	s_xor_b32 vcc_lo, vcc_lo, 0xaaaaaaaa
	s_xor_b32 vcc_hi, vcc_hi, 0xaaaaaaaa
	v_cndmask_b32_dpp v9, v8, v8, vcc quad_perm:[1,0,3,2] row_mask:0xf bank_mask:0xf
	v_xor_b32_e32 v253, 63, v81
	v_lshlrev_b32_e32 v253, 2, v253
	ds_bpermute_b32 v252, v253, v9
	s_waitcnt lgkmcnt(0)
	v_max_u32_dpp v8, v252, v9 quad_perm:[0,1,2,3] row_mask:0x3 bank_mask:0xf
	v_min_u32_dpp v8, v252, v9 quad_perm:[0,1,2,3] row_mask:0xc bank_mask:0xf
	ds_swizzle_b32 v252, v8 offset:0x401f
	s_waitcnt lgkmcnt(0)
	v_max_u32_dpp v9, v252, v8 quad_perm:[0,1,2,3] row_mask:0x5 bank_mask:0xf
	v_min_u32_dpp v9, v252, v8 quad_perm:[0,1,2,3] row_mask:0xa bank_mask:0xf
	s_nop 1
	v_max_u32_dpp v8, v9, v9 row_ror:8 row_mask:0xf bank_mask:0x3
	v_min_u32_dpp v8, v9, v9 row_ror:8 row_mask:0xf bank_mask:0xc
	s_nop 1
	v_max_u32_dpp v9, v8, v8 row_ror:12 row_mask:0xf bank_mask:0x5
	v_min_u32_dpp v9, v8, v8 row_ror:4 row_mask:0xf bank_mask:0xa
	s_nop 1
	v_sub_co_u32_dpp v250, vcc, v9, v9 quad_perm:[2,3,0,1] row_mask:0xf bank_mask:0xf
	s_xor_b32 vcc_lo, vcc_lo, 0xcccccccc
	s_xor_b32 vcc_hi, vcc_hi, 0xcccccccc
	v_cndmask_b32_dpp v8, v9, v9, vcc quad_perm:[2,3,0,1] row_mask:0xf bank_mask:0xf
	s_nop 1
	v_sub_co_u32_dpp v250, vcc, v8, v8 quad_perm:[1,0,3,2] row_mask:0xf bank_mask:0xf
	s_xor_b32 vcc_lo, vcc_lo, 0xaaaaaaaa
	s_xor_b32 vcc_hi, vcc_hi, 0xaaaaaaaa
	v_cndmask_b32_dpp v9, v8, v8, vcc quad_perm:[1,0,3,2] row_mask:0xf bank_mask:0xf
	v_not_b32_e32 v253, v9
	v_and_b32_e32 v253, 63, v253
	v_lshlrev_b32_e32 v253, 2, v253
	ds_permute_b32 v8, v253, v81
	s_waitcnt lgkmcnt(0)
	v_lshlrev_b32_e32 v10, 3, v8
	v_lshlrev_b32_e32 v9, 7, v8
	v_and_b32_e32 v10, 0x70, v10
	v_and_or_b32 v9, v9, s43, v10
	v_cmp_gt_u32_e32 vcc, 16, v8
	v_and_b32_e32 v10, 0x7f, v16
	s_nop 0
	v_cndmask_b32_e32 v8, 4, v9, vcc
	ds_permute_b32 v2, v8, v2
	s_waitcnt lgkmcnt(0)
	v_readlane_b32 s2, v2, 0
	s_nop 1
	v_subrev_f32_e32 v2, s2, v2
	v_mul_f32_e32 v2, 0x3fb8aa3b, v2
	v_exp_f32_e32 v2, v2
	s_nop 0
	v_cndmask_b32_e64 v7, 0, v2, s[12:13]
	ds_bpermute_b32 v1, v240, v7
	v_add_f32_e32 v2, v4, v5
	v_div_scale_f32 v4, s[2:3], v2, v2, v3
	v_rcp_f32_e32 v5, v4
	s_waitcnt lgkmcnt(0)
	v_add_f32_e32 v1, v7, v1
	ds_bpermute_b32 v9, v241, v1
	v_fma_f32 v11, -v4, v5, 1.0
	v_fmac_f32_e32 v5, v11, v5
	v_div_scale_f32 v11, vcc, v3, v2, v3
	s_waitcnt lgkmcnt(0)
	v_add_f32_e32 v1, v1, v9
	ds_bpermute_b32 v9, v242, v1
	v_mul_f32_e32 v12, v11, v5
	v_fma_f32 v13, -v4, v12, v11
	v_fmac_f32_e32 v12, v13, v5
	v_fma_f32 v4, -v4, v12, v11
	s_waitcnt lgkmcnt(0)
	v_add_f32_e32 v1, v1, v9
	ds_bpermute_b32 v9, v243, v1
	v_div_fmas_f32 v4, v4, v5, v12
	s_waitcnt lgkmcnt(0)
	v_add_f32_e32 v5, v1, v9
	v_div_scale_f32 v9, s[2:3], v5, v5, v7
	v_rcp_f32_e32 v11, v9
	v_div_fixup_f32 v1, v4, v2, v3
	v_and_or_b32 v2, v6, s44, v10
	ds_permute_b32 v2, v8, v2
	v_fma_f32 v3, -v9, v11, 1.0
	v_fmac_f32_e32 v11, v3, v11
	v_div_scale_f32 v3, vcc, v7, v5, v7
	v_mul_f32_e32 v4, v3, v11
	v_fma_f32 v6, -v9, v4, v3
	v_fmac_f32_e32 v4, v6, v11
	v_fma_f32 v3, -v9, v4, v3
	v_div_fmas_f32 v3, v3, v11, v4
	v_div_fixup_f32 v3, v3, v5, v7
	s_waitcnt lgkmcnt(0)
	ds_write2st64_b64 v239, v[0:1], v[2:3] offset0:6 offset1:7
	s_branch .LBB0_330
.LBB0_329:
	s_or_b64 exec, exec, s[2:3]
	v_mad_i64_i32 v[0:1], s[2:3], v0, s28, 0
	v_mad_i64_i32 v[4:5], s[2:3], v2, s28, 0
	v_mad_i64_i32 v[2:3], s[2:3], v3, s28, 0
	v_mad_i64_i32 v[8:9], s[2:3], v6, s28, 0
	v_mad_i64_i32 v[6:7], s[2:3], v7, s28, 0
	v_mad_i64_i32 v[12:13], s[2:3], v10, s28, 0
	v_mad_i64_i32 v[10:11], s[2:3], v11, s28, 0
	v_mad_i64_i32 v[14:15], s[2:3], v14, s28, 0
	s_brev_b32 s2, -2
	s_nop 0
	v_bfi_b32 v16, s2, v19, v16
	v_mul_f32_e32 v18, 0.5, v18
	v_add_f32_e32 v16, 1.0, v16
	v_mul_f32_e32 v16, v18, v16
	v_mul_f32_e32 v16, v17, v16
	v_mul_f32_e32 v117, 0x3daaaaab, v16
	ds_bpermute_b32 v250, v255, v117
	s_nop 0
	s_waitcnt vmcnt(23)
	v_cvt_scalef32_pk_f32_fp4 v[18:19], v110, 1.0
	s_waitcnt lgkmcnt(0)
	ds_bpermute_b32 v252, v255, v117 offset:16
	v_cvt_scalef32_pk_f32_fp4 v[20:21], v110, 1.0 op_sel:[1,0,0]
	v_cvt_scalef32_pk_f32_fp4 v[22:23], v110, 1.0 op_sel:[0,1,0]
	v_cvt_scalef32_pk_f32_fp4 v[24:25], v110, 1.0 op_sel:[1,1,0]
	v_cvt_scalef32_pk_f32_fp4 v[26:27], v111, 1.0
	v_cvt_scalef32_pk_f32_fp4 v[28:29], v111, 1.0 op_sel:[1,0,0]
	v_cvt_scalef32_pk_f32_fp4 v[30:31], v111, 1.0 op_sel:[0,1,0]
	v_cvt_scalef32_pk_f32_fp4 v[110:111], v111, 1.0 op_sel:[1,1,0]
	v_pk_fma_f32 v[110:111], v[250:251], v[110:111], v[202:203] op_sel_hi:[0,1,1]
	v_cvt_scalef32_pk_f32_fp4 v[202:203], v112, 1.0
	v_pk_fma_f32 v[200:201], v[250:251], v[202:203], v[200:201] op_sel_hi:[0,1,1]
	v_cvt_scalef32_pk_f32_fp4 v[202:203], v112, 1.0 op_sel:[1,0,0]
	v_pk_fma_f32 v[198:199], v[250:251], v[202:203], v[198:199] op_sel_hi:[0,1,1]
	v_cvt_scalef32_pk_f32_fp4 v[202:203], v112, 1.0 op_sel:[0,1,0]
	v_pk_fma_f32 v[196:197], v[250:251], v[202:203], v[196:197] op_sel_hi:[0,1,1]
	v_cvt_scalef32_pk_f32_fp4 v[202:203], v112, 1.0 op_sel:[1,1,0]
	v_pk_fma_f32 v[194:195], v[250:251], v[202:203], v[194:195] op_sel_hi:[0,1,1]
	v_cvt_scalef32_pk_f32_fp4 v[202:203], v113, 1.0
	v_pk_fma_f32 v[192:193], v[250:251], v[202:203], v[192:193] op_sel_hi:[0,1,1]
	v_cvt_scalef32_pk_f32_fp4 v[202:203], v113, 1.0 op_sel:[1,0,0]
	v_pk_fma_f32 v[190:191], v[250:251], v[202:203], v[190:191] op_sel_hi:[0,1,1]
	v_cvt_scalef32_pk_f32_fp4 v[202:203], v113, 1.0 op_sel:[0,1,0]
	v_pk_fma_f32 v[188:189], v[250:251], v[202:203], v[188:189] op_sel_hi:[0,1,1]
	v_cvt_scalef32_pk_f32_fp4 v[112:113], v113, 1.0 op_sel:[1,1,0]
	v_pk_fma_f32 v[18:19], v[18:19], v[250:251], v[216:217] op_sel_hi:[1,0,1]
	v_pk_fma_f32 v[20:21], v[20:21], v[250:251], v[214:215] op_sel_hi:[1,0,1]
	v_pk_fma_f32 v[22:23], v[22:23], v[250:251], v[212:213] op_sel_hi:[1,0,1]
	v_pk_fma_f32 v[24:25], v[250:251], v[24:25], v[210:211] op_sel_hi:[0,1,1]
	v_pk_fma_f32 v[26:27], v[250:251], v[26:27], v[208:209] op_sel_hi:[0,1,1]
	v_pk_fma_f32 v[28:29], v[250:251], v[28:29], v[206:207] op_sel_hi:[0,1,1]
	v_pk_fma_f32 v[30:31], v[250:251], v[30:31], v[204:205] op_sel_hi:[0,1,1]
	v_pk_fma_f32 v[16:17], v[250:251], v[112:113], v[176:177] op_sel_hi:[0,1,1]
	s_waitcnt vmcnt(22)
	v_cvt_scalef32_pk_f32_fp4 v[176:177], v106, 1.0
	s_waitcnt lgkmcnt(0)
	ds_bpermute_b32 v250, v255, v117 offset:32
	v_pk_fma_f32 v[18:19], v[176:177], v[252:253], v[18:19] op_sel_hi:[1,0,1]
	v_cvt_scalef32_pk_f32_fp4 v[176:177], v106, 1.0 op_sel:[1,0,0]
	v_pk_fma_f32 v[20:21], v[176:177], v[252:253], v[20:21] op_sel_hi:[1,0,1]
	v_cvt_scalef32_pk_f32_fp4 v[176:177], v106, 1.0 op_sel:[0,1,0]
	v_pk_fma_f32 v[22:23], v[176:177], v[252:253], v[22:23] op_sel_hi:[1,0,1]
	v_cvt_scalef32_pk_f32_fp4 v[176:177], v106, 1.0 op_sel:[1,1,0]
	v_pk_fma_f32 v[24:25], v[252:253], v[176:177], v[24:25] op_sel_hi:[0,1,1]
	v_cvt_scalef32_pk_f32_fp4 v[176:177], v107, 1.0
	v_pk_fma_f32 v[26:27], v[252:253], v[176:177], v[26:27] op_sel_hi:[0,1,1]
	v_cvt_scalef32_pk_f32_fp4 v[176:177], v107, 1.0 op_sel:[1,0,0]
	v_pk_fma_f32 v[28:29], v[252:253], v[176:177], v[28:29] op_sel_hi:[0,1,1]
	v_cvt_scalef32_pk_f32_fp4 v[176:177], v107, 1.0 op_sel:[0,1,0]
	v_pk_fma_f32 v[30:31], v[252:253], v[176:177], v[30:31] op_sel_hi:[0,1,1]
	v_cvt_scalef32_pk_f32_fp4 v[176:177], v108, 1.0 op_sel:[1,0,0]
	v_pk_fma_f32 v[176:177], v[252:253], v[176:177], v[198:199] op_sel_hi:[0,1,1]
	v_cvt_scalef32_pk_f32_fp4 v[198:199], v108, 1.0 op_sel:[0,1,0]
	v_pk_fma_f32 v[196:197], v[252:253], v[198:199], v[196:197] op_sel_hi:[0,1,1]
	v_cvt_scalef32_pk_f32_fp4 v[198:199], v108, 1.0 op_sel:[1,1,0]
	v_pk_fma_f32 v[194:195], v[252:253], v[198:199], v[194:195] op_sel_hi:[0,1,1]
	v_cvt_scalef32_pk_f32_fp4 v[198:199], v109, 1.0
	v_cvt_scalef32_pk_f32_fp4 v[106:107], v107, 1.0 op_sel:[1,1,0]
	v_pk_fma_f32 v[192:193], v[252:253], v[198:199], v[192:193] op_sel_hi:[0,1,1]
	v_cvt_scalef32_pk_f32_fp4 v[198:199], v109, 1.0 op_sel:[1,0,0]
	v_pk_fma_f32 v[106:107], v[252:253], v[106:107], v[110:111] op_sel_hi:[0,1,1]
	v_cvt_scalef32_pk_f32_fp4 v[110:111], v108, 1.0
	v_pk_fma_f32 v[190:191], v[252:253], v[198:199], v[190:191] op_sel_hi:[0,1,1]
	v_cvt_scalef32_pk_f32_fp4 v[198:199], v109, 1.0 op_sel:[0,1,0]
	v_pk_fma_f32 v[110:111], v[252:253], v[110:111], v[200:201] op_sel_hi:[0,1,1]
	v_pk_fma_f32 v[188:189], v[252:253], v[198:199], v[188:189] op_sel_hi:[0,1,1]
	v_cvt_scalef32_pk_f32_fp4 v[108:109], v109, 1.0 op_sel:[1,1,0]
	v_pk_fma_f32 v[16:17], v[252:253], v[108:109], v[16:17] op_sel_hi:[0,1,1]
	s_waitcnt vmcnt(21)
	v_cvt_scalef32_pk_f32_fp4 v[112:113], v102, 1.0
	s_waitcnt lgkmcnt(0)
	ds_bpermute_b32 v252, v255, v117 offset:48
	v_pk_fma_f32 v[18:19], v[112:113], v[250:251], v[18:19] op_sel_hi:[1,0,1]
	v_cvt_scalef32_pk_f32_fp4 v[112:113], v102, 1.0 op_sel:[1,0,0]
	v_pk_fma_f32 v[20:21], v[112:113], v[250:251], v[20:21] op_sel_hi:[1,0,1]
	v_cvt_scalef32_pk_f32_fp4 v[112:113], v102, 1.0 op_sel:[0,1,0]
	v_pk_fma_f32 v[22:23], v[112:113], v[250:251], v[22:23] op_sel_hi:[1,0,1]
	v_cvt_scalef32_pk_f32_fp4 v[112:113], v102, 1.0 op_sel:[1,1,0]
	v_pk_fma_f32 v[24:25], v[250:251], v[112:113], v[24:25] op_sel_hi:[0,1,1]
	v_cvt_scalef32_pk_f32_fp4 v[112:113], v103, 1.0
	v_pk_fma_f32 v[26:27], v[250:251], v[112:113], v[26:27] op_sel_hi:[0,1,1]
	v_cvt_scalef32_pk_f32_fp4 v[112:113], v103, 1.0 op_sel:[1,0,0]
	v_pk_fma_f32 v[28:29], v[250:251], v[112:113], v[28:29] op_sel_hi:[0,1,1]
	v_cvt_scalef32_pk_f32_fp4 v[112:113], v103, 1.0 op_sel:[0,1,0]
	v_cvt_scalef32_pk_f32_fp4 v[102:103], v103, 1.0 op_sel:[1,1,0]
	v_pk_fma_f32 v[102:103], v[250:251], v[102:103], v[106:107] op_sel_hi:[0,1,1]
	v_cvt_scalef32_pk_f32_fp4 v[106:107], v104, 1.0
	v_pk_fma_f32 v[106:107], v[250:251], v[106:107], v[110:111] op_sel_hi:[0,1,1]
	v_cvt_scalef32_pk_f32_fp4 v[110:111], v104, 1.0 op_sel:[1,0,0]
	v_pk_fma_f32 v[110:111], v[250:251], v[110:111], v[176:177] op_sel_hi:[0,1,1]
	v_cvt_scalef32_pk_f32_fp4 v[176:177], v104, 1.0 op_sel:[1,1,0]
	v_pk_fma_f32 v[176:177], v[250:251], v[176:177], v[194:195] op_sel_hi:[0,1,1]
	v_cvt_scalef32_pk_f32_fp4 v[194:195], v105, 1.0
	v_pk_fma_f32 v[192:193], v[250:251], v[194:195], v[192:193] op_sel_hi:[0,1,1]
	v_cvt_scalef32_pk_f32_fp4 v[194:195], v105, 1.0 op_sel:[1,0,0]
	v_pk_fma_f32 v[30:31], v[250:251], v[112:113], v[30:31] op_sel_hi:[0,1,1]
	v_cvt_scalef32_pk_f32_fp4 v[112:113], v104, 1.0 op_sel:[0,1,0]
	v_pk_fma_f32 v[190:191], v[250:251], v[194:195], v[190:191] op_sel_hi:[0,1,1]
	v_cvt_scalef32_pk_f32_fp4 v[194:195], v105, 1.0 op_sel:[0,1,0]
	v_pk_fma_f32 v[112:113], v[250:251], v[112:113], v[196:197] op_sel_hi:[0,1,1]
	v_pk_fma_f32 v[188:189], v[250:251], v[194:195], v[188:189] op_sel_hi:[0,1,1]
	v_cvt_scalef32_pk_f32_fp4 v[104:105], v105, 1.0 op_sel:[1,1,0]
	v_pk_fma_f32 v[16:17], v[250:251], v[104:105], v[16:17] op_sel_hi:[0,1,1]
	s_waitcnt vmcnt(20)
	v_cvt_scalef32_pk_f32_fp4 v[108:109], v98, 1.0
	s_waitcnt lgkmcnt(0)
	ds_bpermute_b32 v250, v255, v117 offset:64
	v_pk_fma_f32 v[18:19], v[108:109], v[252:253], v[18:19] op_sel_hi:[1,0,1]
	v_cvt_scalef32_pk_f32_fp4 v[108:109], v98, 1.0 op_sel:[1,0,0]
	v_pk_fma_f32 v[20:21], v[108:109], v[252:253], v[20:21] op_sel_hi:[1,0,1]
	v_cvt_scalef32_pk_f32_fp4 v[108:109], v98, 1.0 op_sel:[0,1,0]
	v_pk_fma_f32 v[22:23], v[108:109], v[252:253], v[22:23] op_sel_hi:[1,0,1]
	v_cvt_scalef32_pk_f32_fp4 v[108:109], v98, 1.0 op_sel:[1,1,0]
	v_pk_fma_f32 v[24:25], v[252:253], v[108:109], v[24:25] op_sel_hi:[0,1,1]
	v_cvt_scalef32_pk_f32_fp4 v[108:109], v99, 1.0
	v_pk_fma_f32 v[26:27], v[252:253], v[108:109], v[26:27] op_sel_hi:[0,1,1]
	v_cvt_scalef32_pk_f32_fp4 v[108:109], v99, 1.0 op_sel:[1,0,0]
	v_pk_fma_f32 v[28:29], v[252:253], v[108:109], v[28:29] op_sel_hi:[0,1,1]
	v_cvt_scalef32_pk_f32_fp4 v[108:109], v99, 1.0 op_sel:[0,1,0]
	v_cvt_scalef32_pk_f32_fp4 v[98:99], v99, 1.0 op_sel:[1,1,0]
	v_pk_fma_f32 v[98:99], v[252:253], v[98:99], v[102:103] op_sel_hi:[0,1,1]
	v_cvt_scalef32_pk_f32_fp4 v[102:103], v100, 1.0
	v_pk_fma_f32 v[102:103], v[252:253], v[102:103], v[106:107] op_sel_hi:[0,1,1]
	v_cvt_scalef32_pk_f32_fp4 v[106:107], v100, 1.0 op_sel:[1,0,0]
	v_pk_fma_f32 v[106:107], v[252:253], v[106:107], v[110:111] op_sel_hi:[0,1,1]
	v_cvt_scalef32_pk_f32_fp4 v[110:111], v100, 1.0 op_sel:[1,1,0]
	v_pk_fma_f32 v[30:31], v[252:253], v[108:109], v[30:31] op_sel_hi:[0,1,1]
	v_cvt_scalef32_pk_f32_fp4 v[108:109], v100, 1.0 op_sel:[0,1,0]
	v_pk_fma_f32 v[110:111], v[252:253], v[110:111], v[176:177] op_sel_hi:[0,1,1]
	v_cvt_scalef32_pk_f32_fp4 v[176:177], v101, 1.0 op_sel:[1,0,0]
	v_pk_fma_f32 v[108:109], v[252:253], v[108:109], v[112:113] op_sel_hi:[0,1,1]
	v_cvt_scalef32_pk_f32_fp4 v[112:113], v101, 1.0
	v_pk_fma_f32 v[176:177], v[252:253], v[176:177], v[190:191] op_sel_hi:[0,1,1]
	v_cvt_scalef32_pk_f32_fp4 v[190:191], v101, 1.0 op_sel:[0,1,0]
	v_pk_fma_f32 v[112:113], v[252:253], v[112:113], v[192:193] op_sel_hi:[0,1,1]
	v_pk_fma_f32 v[188:189], v[252:253], v[190:191], v[188:189] op_sel_hi:[0,1,1]
	v_cvt_scalef32_pk_f32_fp4 v[100:101], v101, 1.0 op_sel:[1,1,0]
	v_pk_fma_f32 v[16:17], v[252:253], v[100:101], v[16:17] op_sel_hi:[0,1,1]
	s_waitcnt vmcnt(19)
	v_cvt_scalef32_pk_f32_fp4 v[104:105], v94, 1.0
	s_waitcnt lgkmcnt(0)
	ds_bpermute_b32 v252, v255, v117 offset:80
	v_pk_fma_f32 v[18:19], v[104:105], v[250:251], v[18:19] op_sel_hi:[1,0,1]
	v_cvt_scalef32_pk_f32_fp4 v[104:105], v94, 1.0 op_sel:[1,0,0]
	v_pk_fma_f32 v[20:21], v[104:105], v[250:251], v[20:21] op_sel_hi:[1,0,1]
	v_cvt_scalef32_pk_f32_fp4 v[104:105], v94, 1.0 op_sel:[0,1,0]
	v_pk_fma_f32 v[22:23], v[104:105], v[250:251], v[22:23] op_sel_hi:[1,0,1]
	v_cvt_scalef32_pk_f32_fp4 v[104:105], v94, 1.0 op_sel:[1,1,0]
	v_pk_fma_f32 v[24:25], v[250:251], v[104:105], v[24:25] op_sel_hi:[0,1,1]
	v_cvt_scalef32_pk_f32_fp4 v[104:105], v95, 1.0
	v_pk_fma_f32 v[26:27], v[250:251], v[104:105], v[26:27] op_sel_hi:[0,1,1]
	v_cvt_scalef32_pk_f32_fp4 v[104:105], v95, 1.0 op_sel:[1,0,0]
	v_pk_fma_f32 v[28:29], v[250:251], v[104:105], v[28:29] op_sel_hi:[0,1,1]
	v_cvt_scalef32_pk_f32_fp4 v[104:105], v95, 1.0 op_sel:[0,1,0]
	v_cvt_scalef32_pk_f32_fp4 v[94:95], v95, 1.0 op_sel:[1,1,0]
	v_pk_fma_f32 v[94:95], v[250:251], v[94:95], v[98:99] op_sel_hi:[0,1,1]
	v_cvt_scalef32_pk_f32_fp4 v[98:99], v96, 1.0
	v_pk_fma_f32 v[30:31], v[250:251], v[104:105], v[30:31] op_sel_hi:[0,1,1]
	v_pk_fma_f32 v[98:99], v[250:251], v[98:99], v[102:103] op_sel_hi:[0,1,1]
	v_cvt_scalef32_pk_f32_fp4 v[102:103], v96, 1.0 op_sel:[1,0,0]
	v_cvt_scalef32_pk_f32_fp4 v[104:105], v96, 1.0 op_sel:[0,1,0]
	v_pk_fma_f32 v[102:103], v[250:251], v[102:103], v[106:107] op_sel_hi:[0,1,1]
	v_pk_fma_f32 v[104:105], v[250:251], v[104:105], v[108:109] op_sel_hi:[0,1,1]
	v_cvt_scalef32_pk_f32_fp4 v[106:107], v96, 1.0 op_sel:[1,1,0]
	v_cvt_scalef32_pk_f32_fp4 v[108:109], v97, 1.0
	v_pk_fma_f32 v[106:107], v[250:251], v[106:107], v[110:111] op_sel_hi:[0,1,1]
	v_pk_fma_f32 v[108:109], v[250:251], v[108:109], v[112:113] op_sel_hi:[0,1,1]
	v_cvt_scalef32_pk_f32_fp4 v[110:111], v97, 1.0 op_sel:[1,0,0]
	v_cvt_scalef32_pk_f32_fp4 v[112:113], v97, 1.0 op_sel:[0,1,0]
	v_pk_fma_f32 v[110:111], v[250:251], v[110:111], v[176:177] op_sel_hi:[0,1,1]
	v_pk_fma_f32 v[112:113], v[250:251], v[112:113], v[188:189] op_sel_hi:[0,1,1]
	v_cvt_scalef32_pk_f32_fp4 v[96:97], v97, 1.0 op_sel:[1,1,0]
	v_pk_fma_f32 v[16:17], v[250:251], v[96:97], v[16:17] op_sel_hi:[0,1,1]
	s_waitcnt vmcnt(18)
	v_cvt_scalef32_pk_f32_fp4 v[100:101], v90, 1.0
	s_waitcnt lgkmcnt(0)
	ds_bpermute_b32 v250, v255, v117 offset:96
	v_pk_fma_f32 v[18:19], v[100:101], v[252:253], v[18:19] op_sel_hi:[1,0,1]
	v_cvt_scalef32_pk_f32_fp4 v[100:101], v90, 1.0 op_sel:[1,0,0]
	v_pk_fma_f32 v[20:21], v[100:101], v[252:253], v[20:21] op_sel_hi:[1,0,1]
	v_cvt_scalef32_pk_f32_fp4 v[100:101], v90, 1.0 op_sel:[0,1,0]
	v_pk_fma_f32 v[22:23], v[100:101], v[252:253], v[22:23] op_sel_hi:[1,0,1]
	v_cvt_scalef32_pk_f32_fp4 v[100:101], v90, 1.0 op_sel:[1,1,0]
	v_pk_fma_f32 v[24:25], v[252:253], v[100:101], v[24:25] op_sel_hi:[0,1,1]
	v_cvt_scalef32_pk_f32_fp4 v[100:101], v91, 1.0
	v_pk_fma_f32 v[26:27], v[252:253], v[100:101], v[26:27] op_sel_hi:[0,1,1]
	v_cvt_scalef32_pk_f32_fp4 v[100:101], v91, 1.0 op_sel:[1,0,0]
	v_pk_fma_f32 v[28:29], v[252:253], v[100:101], v[28:29] op_sel_hi:[0,1,1]
	v_cvt_scalef32_pk_f32_fp4 v[100:101], v91, 1.0 op_sel:[0,1,0]
	v_cvt_scalef32_pk_f32_fp4 v[90:91], v91, 1.0 op_sel:[1,1,0]
	v_pk_fma_f32 v[90:91], v[252:253], v[90:91], v[94:95] op_sel_hi:[0,1,1]
	v_cvt_scalef32_pk_f32_fp4 v[94:95], v92, 1.0
	v_pk_fma_f32 v[30:31], v[252:253], v[100:101], v[30:31] op_sel_hi:[0,1,1]
	v_pk_fma_f32 v[94:95], v[252:253], v[94:95], v[98:99] op_sel_hi:[0,1,1]
	v_cvt_scalef32_pk_f32_fp4 v[98:99], v92, 1.0 op_sel:[1,0,0]
	v_cvt_scalef32_pk_f32_fp4 v[100:101], v92, 1.0 op_sel:[0,1,0]
	v_pk_fma_f32 v[98:99], v[252:253], v[98:99], v[102:103] op_sel_hi:[0,1,1]
	v_pk_fma_f32 v[100:101], v[252:253], v[100:101], v[104:105] op_sel_hi:[0,1,1]
	v_cvt_scalef32_pk_f32_fp4 v[102:103], v92, 1.0 op_sel:[1,1,0]
	v_cvt_scalef32_pk_f32_fp4 v[104:105], v93, 1.0
	v_pk_fma_f32 v[102:103], v[252:253], v[102:103], v[106:107] op_sel_hi:[0,1,1]
	v_pk_fma_f32 v[104:105], v[252:253], v[104:105], v[108:109] op_sel_hi:[0,1,1]
	v_cvt_scalef32_pk_f32_fp4 v[106:107], v93, 1.0 op_sel:[1,0,0]
	v_cvt_scalef32_pk_f32_fp4 v[108:109], v93, 1.0 op_sel:[0,1,0]
	v_pk_fma_f32 v[106:107], v[252:253], v[106:107], v[110:111] op_sel_hi:[0,1,1]
	v_pk_fma_f32 v[108:109], v[252:253], v[108:109], v[112:113] op_sel_hi:[0,1,1]
	v_cvt_scalef32_pk_f32_fp4 v[92:93], v93, 1.0 op_sel:[1,1,0]
	v_pk_fma_f32 v[16:17], v[252:253], v[92:93], v[16:17] op_sel_hi:[0,1,1]
	s_waitcnt vmcnt(17)
	v_cvt_scalef32_pk_f32_fp4 v[96:97], v86, 1.0
	s_waitcnt lgkmcnt(0)
	ds_bpermute_b32 v252, v255, v117 offset:112
	v_pk_fma_f32 v[18:19], v[96:97], v[250:251], v[18:19] op_sel_hi:[1,0,1]
	v_cvt_scalef32_pk_f32_fp4 v[96:97], v86, 1.0 op_sel:[1,0,0]
	v_pk_fma_f32 v[20:21], v[96:97], v[250:251], v[20:21] op_sel_hi:[1,0,1]
	v_cvt_scalef32_pk_f32_fp4 v[96:97], v86, 1.0 op_sel:[0,1,0]
	v_pk_fma_f32 v[22:23], v[96:97], v[250:251], v[22:23] op_sel_hi:[1,0,1]
	v_cvt_scalef32_pk_f32_fp4 v[96:97], v86, 1.0 op_sel:[1,1,0]
	v_pk_fma_f32 v[24:25], v[250:251], v[96:97], v[24:25] op_sel_hi:[0,1,1]
	v_cvt_scalef32_pk_f32_fp4 v[96:97], v87, 1.0
	v_pk_fma_f32 v[26:27], v[250:251], v[96:97], v[26:27] op_sel_hi:[0,1,1]
	v_cvt_scalef32_pk_f32_fp4 v[96:97], v87, 1.0 op_sel:[1,0,0]
	v_pk_fma_f32 v[28:29], v[250:251], v[96:97], v[28:29] op_sel_hi:[0,1,1]
	v_cvt_scalef32_pk_f32_fp4 v[96:97], v87, 1.0 op_sel:[0,1,0]
	v_cvt_scalef32_pk_f32_fp4 v[86:87], v87, 1.0 op_sel:[1,1,0]
	v_pk_fma_f32 v[86:87], v[250:251], v[86:87], v[90:91] op_sel_hi:[0,1,1]
	v_cvt_scalef32_pk_f32_fp4 v[90:91], v88, 1.0
	v_pk_fma_f32 v[30:31], v[250:251], v[96:97], v[30:31] op_sel_hi:[0,1,1]
	v_pk_fma_f32 v[90:91], v[250:251], v[90:91], v[94:95] op_sel_hi:[0,1,1]
	v_cvt_scalef32_pk_f32_fp4 v[94:95], v88, 1.0 op_sel:[1,0,0]
	v_cvt_scalef32_pk_f32_fp4 v[96:97], v88, 1.0 op_sel:[0,1,0]
	v_pk_fma_f32 v[94:95], v[250:251], v[94:95], v[98:99] op_sel_hi:[0,1,1]
	v_pk_fma_f32 v[96:97], v[250:251], v[96:97], v[100:101] op_sel_hi:[0,1,1]
	v_cvt_scalef32_pk_f32_fp4 v[98:99], v88, 1.0 op_sel:[1,1,0]
	v_cvt_scalef32_pk_f32_fp4 v[100:101], v89, 1.0
	v_pk_fma_f32 v[98:99], v[250:251], v[98:99], v[102:103] op_sel_hi:[0,1,1]
	v_pk_fma_f32 v[100:101], v[250:251], v[100:101], v[104:105] op_sel_hi:[0,1,1]
	v_cvt_scalef32_pk_f32_fp4 v[102:103], v89, 1.0 op_sel:[1,0,0]
	v_cvt_scalef32_pk_f32_fp4 v[104:105], v89, 1.0 op_sel:[0,1,0]
	v_pk_fma_f32 v[102:103], v[250:251], v[102:103], v[106:107] op_sel_hi:[0,1,1]
	v_pk_fma_f32 v[104:105], v[250:251], v[104:105], v[108:109] op_sel_hi:[0,1,1]
	v_cvt_scalef32_pk_f32_fp4 v[88:89], v89, 1.0 op_sel:[1,1,0]
	v_pk_fma_f32 v[16:17], v[250:251], v[88:89], v[16:17] op_sel_hi:[0,1,1]
	s_waitcnt vmcnt(16)
	v_cvt_scalef32_pk_f32_fp4 v[92:93], v82, 1.0
	s_waitcnt lgkmcnt(0)
	v_pk_fma_f32 v[216:217], v[92:93], v[252:253], v[18:19] op_sel_hi:[1,0,1]
	v_cvt_scalef32_pk_f32_fp4 v[18:19], v82, 1.0 op_sel:[1,0,0]
	v_pk_fma_f32 v[214:215], v[18:19], v[252:253], v[20:21] op_sel_hi:[1,0,1]
	v_cvt_scalef32_pk_f32_fp4 v[18:19], v82, 1.0 op_sel:[0,1,0]
	v_pk_fma_f32 v[212:213], v[18:19], v[252:253], v[22:23] op_sel_hi:[1,0,1]
	v_cvt_scalef32_pk_f32_fp4 v[18:19], v82, 1.0 op_sel:[1,1,0]
	v_pk_fma_f32 v[210:211], v[252:253], v[18:19], v[24:25] op_sel_hi:[0,1,1]
	v_cvt_scalef32_pk_f32_fp4 v[18:19], v83, 1.0
	v_pk_fma_f32 v[208:209], v[252:253], v[18:19], v[26:27] op_sel_hi:[0,1,1]
	v_cvt_scalef32_pk_f32_fp4 v[18:19], v83, 1.0 op_sel:[1,0,0]
	v_pk_fma_f32 v[206:207], v[252:253], v[18:19], v[28:29] op_sel_hi:[0,1,1]
	v_cvt_scalef32_pk_f32_fp4 v[18:19], v83, 1.0 op_sel:[0,1,0]
	v_pk_fma_f32 v[204:205], v[252:253], v[18:19], v[30:31] op_sel_hi:[0,1,1]
	v_cvt_scalef32_pk_f32_fp4 v[18:19], v83, 1.0 op_sel:[1,1,0]
	v_pk_fma_f32 v[202:203], v[252:253], v[18:19], v[86:87] op_sel_hi:[0,1,1]
	v_cvt_scalef32_pk_f32_fp4 v[18:19], v84, 1.0
	v_pk_fma_f32 v[200:201], v[252:253], v[18:19], v[90:91] op_sel_hi:[0,1,1]
	v_cvt_scalef32_pk_f32_fp4 v[18:19], v84, 1.0 op_sel:[1,0,0]
	v_pk_fma_f32 v[198:199], v[252:253], v[18:19], v[94:95] op_sel_hi:[0,1,1]
	v_cvt_scalef32_pk_f32_fp4 v[18:19], v84, 1.0 op_sel:[0,1,0]
	v_pk_fma_f32 v[196:197], v[252:253], v[18:19], v[96:97] op_sel_hi:[0,1,1]
	v_cvt_scalef32_pk_f32_fp4 v[18:19], v84, 1.0 op_sel:[1,1,0]
	v_pk_fma_f32 v[194:195], v[252:253], v[18:19], v[98:99] op_sel_hi:[0,1,1]
	v_cvt_scalef32_pk_f32_fp4 v[18:19], v85, 1.0
	v_pk_fma_f32 v[192:193], v[252:253], v[18:19], v[100:101] op_sel_hi:[0,1,1]
	v_cvt_scalef32_pk_f32_fp4 v[18:19], v85, 1.0 op_sel:[1,0,0]
	v_pk_fma_f32 v[190:191], v[252:253], v[18:19], v[102:103] op_sel_hi:[0,1,1]
	v_cvt_scalef32_pk_f32_fp4 v[18:19], v85, 1.0 op_sel:[0,1,0]
	v_pk_fma_f32 v[188:189], v[252:253], v[18:19], v[104:105] op_sel_hi:[0,1,1]
	v_cvt_scalef32_pk_f32_fp4 v[18:19], v85, 1.0 op_sel:[1,1,0]
	v_pk_fma_f32 v[176:177], v[252:253], v[18:19], v[16:17] op_sel_hi:[0,1,1]
	v_lshl_add_u64 v[0:1], v[120:121], 0, v[0:1]
	v_lshl_add_u64 v[4:5], v[120:121], 0, v[4:5]
	global_load_dwordx4 v[110:113], v[0:1], off offset:768
	global_load_dwordx4 v[106:109], v[4:5], off offset:768
	v_lshl_add_u64 v[0:1], v[120:121], 0, v[2:3]
	v_lshl_add_u64 v[2:3], v[120:121], 0, v[8:9]
	global_load_dwordx4 v[102:105], v[0:1], off offset:768
	global_load_dwordx4 v[98:101], v[2:3], off offset:768
	v_lshl_add_u64 v[0:1], v[120:121], 0, v[6:7]
	v_lshl_add_u64 v[2:3], v[120:121], 0, v[12:13]
	global_load_dwordx4 v[94:97], v[0:1], off offset:768
	global_load_dwordx4 v[90:93], v[2:3], off offset:768
	v_lshl_add_u64 v[0:1], v[120:121], 0, v[10:11]
	v_lshl_add_u64 v[2:3], v[120:121], 0, v[14:15]
	global_load_dwordx4 v[86:89], v[0:1], off offset:768
	global_load_dwordx4 v[82:85], v[2:3], off offset:768
	s_addk_i32 s24, 0x200
	s_cmpk_lg_i32 s24, 0xe00
	s_cbranch_scc0 .LBB0_334
.LBB0_330:
	s_waitcnt vmcnt(22)
	v_cvt_scalef32_pk32_f32_fp6 v[0:31], v[32:37], 1.0
	v_pk_fma_f32 v[0:1], v[0:1], v[152:153], 0 op_sel_hi:[1,1,0]
	v_pk_fma_f32 v[2:3], v[2:3], v[170:171], 0 op_sel_hi:[1,1,0]
	v_pk_fma_f32 v[0:1], v[4:5], v[148:149], v[0:1]
	v_pk_fma_f32 v[2:3], v[6:7], v[172:173], v[2:3]
	v_pk_fma_f32 v[0:1], v[8:9], v[144:145], v[0:1]
	v_pk_fma_f32 v[2:3], v[10:11], v[174:175], v[2:3]
	v_pk_fma_f32 v[0:1], v[12:13], v[140:141], v[0:1]
	v_pk_fma_f32 v[2:3], v[14:15], v[178:179], v[2:3]
	v_pk_fma_f32 v[0:1], v[16:17], v[168:169], v[0:1]
	v_pk_fma_f32 v[2:3], v[18:19], v[180:181], v[2:3]
	v_pk_fma_f32 v[0:1], v[20:21], v[164:165], v[0:1]
	v_pk_fma_f32 v[2:3], v[22:23], v[182:183], v[2:3]
	v_pk_fma_f32 v[0:1], v[24:25], v[160:161], v[0:1]
	v_pk_fma_f32 v[2:3], v[26:27], v[184:185], v[2:3]
	v_pk_fma_f32 v[0:1], v[28:29], v[156:157], v[0:1]
	v_pk_fma_f32 v[2:3], v[30:31], v[186:187], v[2:3]
	v_add_f32_e32 v4, v2, v3
	v_add_f32_e32 v5, v0, v1
	v_add_f32_e32 v117, v4, v5
	s_waitcnt vmcnt(20)
	v_cvt_scalef32_pk32_f32_fp6 v[0:31], v[38:43], 1.0
	v_pk_fma_f32 v[0:1], v[0:1], v[152:153], 0 op_sel_hi:[1,1,0]
	v_pk_fma_f32 v[2:3], v[2:3], v[170:171], 0 op_sel_hi:[1,1,0]
	v_pk_fma_f32 v[0:1], v[4:5], v[148:149], v[0:1]
	v_pk_fma_f32 v[2:3], v[6:7], v[172:173], v[2:3]
	v_pk_fma_f32 v[0:1], v[8:9], v[144:145], v[0:1]
	v_pk_fma_f32 v[2:3], v[10:11], v[174:175], v[2:3]
	v_pk_fma_f32 v[0:1], v[12:13], v[140:141], v[0:1]
	v_pk_fma_f32 v[2:3], v[14:15], v[178:179], v[2:3]
	v_pk_fma_f32 v[0:1], v[16:17], v[168:169], v[0:1]
	v_pk_fma_f32 v[2:3], v[18:19], v[180:181], v[2:3]
	v_pk_fma_f32 v[0:1], v[20:21], v[164:165], v[0:1]
	v_pk_fma_f32 v[2:3], v[22:23], v[182:183], v[2:3]
	v_pk_fma_f32 v[0:1], v[24:25], v[160:161], v[0:1]
	v_pk_fma_f32 v[2:3], v[26:27], v[184:185], v[2:3]
	v_pk_fma_f32 v[0:1], v[28:29], v[156:157], v[0:1]
	v_pk_fma_f32 v[2:3], v[30:31], v[186:187], v[2:3]
	v_add_f32_e32 v4, v2, v3
	v_add_f32_e32 v5, v0, v1
	v_add_f32_e32 v131, v4, v5
	s_waitcnt vmcnt(18)
	v_cvt_scalef32_pk32_f32_fp6 v[0:31], v[44:49], 1.0
	v_pk_fma_f32 v[0:1], v[0:1], v[152:153], 0 op_sel_hi:[1,1,0]
	v_pk_fma_f32 v[2:3], v[2:3], v[170:171], 0 op_sel_hi:[1,1,0]
	v_pk_fma_f32 v[0:1], v[4:5], v[148:149], v[0:1]
	v_pk_fma_f32 v[2:3], v[6:7], v[172:173], v[2:3]
	v_pk_fma_f32 v[0:1], v[8:9], v[144:145], v[0:1]
	v_pk_fma_f32 v[2:3], v[10:11], v[174:175], v[2:3]
	v_pk_fma_f32 v[0:1], v[12:13], v[140:141], v[0:1]
	v_pk_fma_f32 v[2:3], v[14:15], v[178:179], v[2:3]
	v_pk_fma_f32 v[0:1], v[16:17], v[168:169], v[0:1]
	v_pk_fma_f32 v[2:3], v[18:19], v[180:181], v[2:3]
	v_pk_fma_f32 v[0:1], v[20:21], v[164:165], v[0:1]
	v_pk_fma_f32 v[2:3], v[22:23], v[182:183], v[2:3]
	v_pk_fma_f32 v[0:1], v[24:25], v[160:161], v[0:1]
	v_pk_fma_f32 v[2:3], v[26:27], v[184:185], v[2:3]
	v_pk_fma_f32 v[0:1], v[28:29], v[156:157], v[0:1]
	v_pk_fma_f32 v[2:3], v[30:31], v[186:187], v[2:3]
	v_add_f32_e32 v4, v2, v3
	v_add_f32_e32 v5, v0, v1
	v_add_f32_e32 v133, v4, v5
	s_waitcnt vmcnt(16)
	v_cvt_scalef32_pk32_f32_fp6 v[0:31], v[50:55], 1.0
	v_pk_fma_f32 v[0:1], v[0:1], v[152:153], 0 op_sel_hi:[1,1,0]
	v_pk_fma_f32 v[2:3], v[2:3], v[170:171], 0 op_sel_hi:[1,1,0]
	v_pk_fma_f32 v[0:1], v[4:5], v[148:149], v[0:1]
	v_pk_fma_f32 v[2:3], v[6:7], v[172:173], v[2:3]
	v_pk_fma_f32 v[0:1], v[8:9], v[144:145], v[0:1]
	v_pk_fma_f32 v[2:3], v[10:11], v[174:175], v[2:3]
	v_pk_fma_f32 v[0:1], v[12:13], v[140:141], v[0:1]
	v_pk_fma_f32 v[2:3], v[14:15], v[178:179], v[2:3]
	v_pk_fma_f32 v[0:1], v[16:17], v[168:169], v[0:1]
	v_pk_fma_f32 v[2:3], v[18:19], v[180:181], v[2:3]
	v_pk_fma_f32 v[0:1], v[20:21], v[164:165], v[0:1]
	v_pk_fma_f32 v[2:3], v[22:23], v[182:183], v[2:3]
	v_pk_fma_f32 v[0:1], v[24:25], v[160:161], v[0:1]
	v_pk_fma_f32 v[2:3], v[26:27], v[184:185], v[2:3]
	v_pk_fma_f32 v[0:1], v[28:29], v[156:157], v[0:1]
	v_pk_fma_f32 v[2:3], v[30:31], v[186:187], v[2:3]
	v_add_f32_e32 v4, v2, v3
	v_add_f32_e32 v5, v0, v1
	v_add_f32_e32 v218, v4, v5
	s_waitcnt vmcnt(14)
	v_cvt_scalef32_pk32_f32_fp6 v[0:31], v[56:61], 1.0
	v_pk_fma_f32 v[0:1], v[0:1], v[152:153], 0 op_sel_hi:[1,1,0]
	v_pk_fma_f32 v[2:3], v[2:3], v[170:171], 0 op_sel_hi:[1,1,0]
	v_pk_fma_f32 v[0:1], v[4:5], v[148:149], v[0:1]
	v_pk_fma_f32 v[2:3], v[6:7], v[172:173], v[2:3]
	v_pk_fma_f32 v[0:1], v[8:9], v[144:145], v[0:1]
	v_pk_fma_f32 v[2:3], v[10:11], v[174:175], v[2:3]
	v_pk_fma_f32 v[0:1], v[12:13], v[140:141], v[0:1]
	v_pk_fma_f32 v[2:3], v[14:15], v[178:179], v[2:3]
	v_pk_fma_f32 v[0:1], v[16:17], v[168:169], v[0:1]
	v_pk_fma_f32 v[2:3], v[18:19], v[180:181], v[2:3]
	v_pk_fma_f32 v[0:1], v[20:21], v[164:165], v[0:1]
	v_pk_fma_f32 v[2:3], v[22:23], v[182:183], v[2:3]
	v_pk_fma_f32 v[0:1], v[24:25], v[160:161], v[0:1]
	v_pk_fma_f32 v[2:3], v[26:27], v[184:185], v[2:3]
	v_pk_fma_f32 v[0:1], v[28:29], v[156:157], v[0:1]
	v_pk_fma_f32 v[2:3], v[30:31], v[186:187], v[2:3]
	v_add_f32_e32 v4, v2, v3
	v_add_f32_e32 v5, v0, v1
	v_add_f32_e32 v219, v4, v5
	s_waitcnt vmcnt(12)
	v_cvt_scalef32_pk32_f32_fp6 v[0:31], v[62:67], 1.0
	v_pk_fma_f32 v[0:1], v[0:1], v[152:153], 0 op_sel_hi:[1,1,0]
	v_pk_fma_f32 v[2:3], v[2:3], v[170:171], 0 op_sel_hi:[1,1,0]
	v_pk_fma_f32 v[0:1], v[4:5], v[148:149], v[0:1]
	v_pk_fma_f32 v[2:3], v[6:7], v[172:173], v[2:3]
	v_pk_fma_f32 v[0:1], v[8:9], v[144:145], v[0:1]
	v_pk_fma_f32 v[2:3], v[10:11], v[174:175], v[2:3]
	v_pk_fma_f32 v[0:1], v[12:13], v[140:141], v[0:1]
	v_pk_fma_f32 v[2:3], v[14:15], v[178:179], v[2:3]
	v_pk_fma_f32 v[0:1], v[16:17], v[168:169], v[0:1]
	v_pk_fma_f32 v[2:3], v[18:19], v[180:181], v[2:3]
	v_pk_fma_f32 v[0:1], v[20:21], v[164:165], v[0:1]
	v_pk_fma_f32 v[2:3], v[22:23], v[182:183], v[2:3]
	v_pk_fma_f32 v[0:1], v[24:25], v[160:161], v[0:1]
	v_pk_fma_f32 v[2:3], v[26:27], v[184:185], v[2:3]
	v_pk_fma_f32 v[0:1], v[28:29], v[156:157], v[0:1]
	v_pk_fma_f32 v[2:3], v[30:31], v[186:187], v[2:3]
	v_add_f32_e32 v4, v2, v3
	v_add_f32_e32 v5, v0, v1
	v_add_f32_e32 v246, v4, v5
	s_waitcnt vmcnt(10)
	v_cvt_scalef32_pk32_f32_fp6 v[0:31], v[68:73], 1.0
	v_pk_fma_f32 v[0:1], v[0:1], v[152:153], 0 op_sel_hi:[1,1,0]
	v_pk_fma_f32 v[2:3], v[2:3], v[170:171], 0 op_sel_hi:[1,1,0]
	v_pk_fma_f32 v[0:1], v[4:5], v[148:149], v[0:1]
	v_pk_fma_f32 v[2:3], v[6:7], v[172:173], v[2:3]
	v_pk_fma_f32 v[0:1], v[8:9], v[144:145], v[0:1]
	v_pk_fma_f32 v[2:3], v[10:11], v[174:175], v[2:3]
	v_pk_fma_f32 v[0:1], v[12:13], v[140:141], v[0:1]
	v_pk_fma_f32 v[2:3], v[14:15], v[178:179], v[2:3]
	v_pk_fma_f32 v[0:1], v[16:17], v[168:169], v[0:1]
	v_pk_fma_f32 v[2:3], v[18:19], v[180:181], v[2:3]
	v_pk_fma_f32 v[0:1], v[20:21], v[164:165], v[0:1]
	v_pk_fma_f32 v[2:3], v[22:23], v[182:183], v[2:3]
	v_pk_fma_f32 v[0:1], v[24:25], v[160:161], v[0:1]
	v_pk_fma_f32 v[2:3], v[26:27], v[184:185], v[2:3]
	v_pk_fma_f32 v[0:1], v[28:29], v[156:157], v[0:1]
	v_pk_fma_f32 v[2:3], v[30:31], v[186:187], v[2:3]
	v_add_f32_e32 v4, v2, v3
	v_add_f32_e32 v5, v0, v1
	v_add_f32_e32 v247, v4, v5
	s_waitcnt vmcnt(8)
	v_cvt_scalef32_pk32_f32_fp6 v[0:31], v[74:79], 1.0
	v_pk_fma_f32 v[0:1], v[0:1], v[152:153], 0 op_sel_hi:[1,1,0]
	v_pk_fma_f32 v[2:3], v[2:3], v[170:171], 0 op_sel_hi:[1,1,0]
	v_pk_fma_f32 v[0:1], v[4:5], v[148:149], v[0:1]
	v_pk_fma_f32 v[2:3], v[6:7], v[172:173], v[2:3]
	v_pk_fma_f32 v[0:1], v[8:9], v[144:145], v[0:1]
	v_pk_fma_f32 v[2:3], v[10:11], v[174:175], v[2:3]
	v_pk_fma_f32 v[0:1], v[12:13], v[140:141], v[0:1]
	v_pk_fma_f32 v[2:3], v[14:15], v[178:179], v[2:3]
	v_pk_fma_f32 v[0:1], v[16:17], v[168:169], v[0:1]
	v_pk_fma_f32 v[2:3], v[18:19], v[180:181], v[2:3]
	v_pk_fma_f32 v[0:1], v[20:21], v[164:165], v[0:1]
	v_pk_fma_f32 v[2:3], v[22:23], v[182:183], v[2:3]
	v_pk_fma_f32 v[0:1], v[24:25], v[160:161], v[0:1]
	v_pk_fma_f32 v[2:3], v[26:27], v[184:185], v[2:3]
	v_pk_fma_f32 v[0:1], v[28:29], v[156:157], v[0:1]
	v_pk_fma_f32 v[2:3], v[30:31], v[186:187], v[2:3]
	v_add_f32_e32 v4, v2, v3
	v_add_f32_e32 v5, v0, v1
	v_add_f32_e32 v1, v4, v5
	v_add_u32_e32 v8, s24, v239
	ds_read_b32 v12, v8 offset:512
	s_waitcnt lgkmcnt(0)
	ds_bpermute_b32 v0, v255, v12
	ds_bpermute_b32 v2, v255, v12 offset:16
	ds_bpermute_b32 v3, v255, v12 offset:32
	ds_bpermute_b32 v6, v255, v12 offset:48
	ds_bpermute_b32 v7, v255, v12 offset:64
	ds_bpermute_b32 v10, v255, v12 offset:80
	ds_bpermute_b32 v11, v255, v12 offset:96
	ds_bpermute_b32 v14, v255, v12 offset:112
	s_waitcnt lgkmcnt(7)
	v_mad_i64_i32 v[22:23], s[2:3], v0, s28, v[118:119]
	global_load_dwordx2 v[36:37], v[22:23], off offset:16
	global_load_dwordx4 v[32:35], v[22:23], off
	s_waitcnt lgkmcnt(6)
	v_mad_i64_i32 v[24:25], s[2:3], v2, s28, v[118:119]
	global_load_dwordx2 v[42:43], v[24:25], off offset:16
	global_load_dwordx4 v[38:41], v[24:25], off
	s_waitcnt lgkmcnt(5)
	v_mad_i64_i32 v[22:23], s[2:3], v3, s28, v[118:119]
	global_load_dwordx2 v[48:49], v[22:23], off offset:16
	global_load_dwordx4 v[44:47], v[22:23], off
	s_waitcnt lgkmcnt(4)
	v_mad_i64_i32 v[24:25], s[2:3], v6, s28, v[118:119]
	global_load_dwordx2 v[54:55], v[24:25], off offset:16
	global_load_dwordx4 v[50:53], v[24:25], off
	s_waitcnt lgkmcnt(3)
	v_mad_i64_i32 v[22:23], s[2:3], v7, s28, v[118:119]
	global_load_dwordx2 v[60:61], v[22:23], off offset:16
	global_load_dwordx4 v[56:59], v[22:23], off
	s_waitcnt lgkmcnt(2)
	v_mad_i64_i32 v[24:25], s[2:3], v10, s28, v[118:119]
	global_load_dwordx2 v[66:67], v[24:25], off offset:16
	global_load_dwordx4 v[62:65], v[24:25], off
	s_waitcnt lgkmcnt(1)
	v_mad_i64_i32 v[22:23], s[2:3], v11, s28, v[118:119]
	global_load_dwordx2 v[72:73], v[22:23], off offset:16
	global_load_dwordx4 v[68:71], v[22:23], off
	s_waitcnt lgkmcnt(0)
	v_mad_i64_i32 v[24:25], s[2:3], v14, s28, v[118:119]
	global_load_dwordx2 v[78:79], v[24:25], off offset:16
	global_load_dwordx4 v[74:77], v[24:25], off
	ds_read_b64 v[16:17], v8
	v_cndmask_b32_e64 v4, v117, v219, s[14:15]
	ds_bpermute_b32 v4, v242, v4
	v_cndmask_b32_e64 v5, v219, v117, s[14:15]
	v_cndmask_b32_e64 v8, v131, v246, s[14:15]
	ds_bpermute_b32 v8, v242, v8
	v_cndmask_b32_e64 v12, v218, v1, s[14:15]
	s_waitcnt lgkmcnt(1)
	v_add_f32_e32 v4, v5, v4
	v_cndmask_b32_e64 v5, v133, v247, s[14:15]
	ds_bpermute_b32 v5, v242, v5
	ds_bpermute_b32 v12, v242, v12
	v_cndmask_b32_e64 v9, v246, v131, s[14:15]
	s_waitcnt lgkmcnt(2)
	v_add_f32_e32 v8, v9, v8
	v_cndmask_b32_e64 v9, v247, v133, s[14:15]
	v_cndmask_b32_e64 v1, v1, v218, s[14:15]
	s_waitcnt lgkmcnt(1)
	v_add_f32_e32 v5, v9, v5
	s_waitcnt lgkmcnt(0)
	v_add_f32_e32 v1, v1, v12
	v_cndmask_b32_e64 v9, v4, v5, s[16:17]
	v_cndmask_b32_e64 v12, v8, v1, s[16:17]
	ds_bpermute_b32 v9, v241, v9
	ds_bpermute_b32 v12, v241, v12
	v_cndmask_b32_e64 v4, v5, v4, s[16:17]
	v_cndmask_b32_e64 v1, v1, v8, s[16:17]
	s_waitcnt lgkmcnt(1)
	v_add_f32_e32 v4, v4, v9
	s_waitcnt lgkmcnt(0)
	v_add_f32_e32 v1, v1, v12
	v_cndmask_b32_e64 v5, v4, v1, s[18:19]
	ds_bpermute_b32 v5, v240, v5
	v_cndmask_b32_e64 v1, v1, v4, s[18:19]
	s_waitcnt lgkmcnt(0)
	v_add_f32_e32 v1, v1, v5
	ds_bpermute_b32 v4, v244, v1
	s_waitcnt lgkmcnt(0)
	v_add_f32_e32 v1, v1, v4
	ds_bpermute_b32 v4, v245, v1
	s_waitcnt lgkmcnt(0)
	v_add_f32_e32 v1, v1, v4
	v_mul_f32_e32 v18, 0x3caaaaab, v1
	v_mul_f32_e32 v16, 0x3f3504f3, v18
	v_cmp_nlt_f32_e64 s[2:3], |v16|, 1.0
	s_and_saveexec_b64 s[26:27], s[2:3]
	s_xor_b64 s[2:3], exec, s[26:27]
	s_cbranch_execz .LBB0_332
	s_mov_b32 s25, 0x378e98ab
	v_fma_f32 v1, |v16|, s25, v233
	s_mov_b32 s25, 0x3b7cd369
	v_fma_f32 v1, |v16|, v1, s25
	s_mov_b32 s25, 0xbcc618b2
	v_fma_f32 v1, |v16|, v1, s25
	s_mov_b32 s25, 0x3dda74e4
	v_fma_f32 v1, |v16|, v1, s25
	s_mov_b32 s25, 0x3f228afd
	v_fma_f32 v1, |v16|, v1, s25
	s_mov_b32 s25, 0x3e03c728
	v_fma_f32 v1, |v16|, v1, s25
	v_fma_f32 v1, |v16|, v1, |v16|
	v_mul_f32_e32 v4, 0xbfb8aa3b, v1
	s_mov_b32 s25, 0xbfb8aa3b
	v_fma_f32 v5, v1, s25, -v4
	v_rndne_f32_e32 v8, v4
	v_fmac_f32_e32 v5, 0xb2a5705f, v1
	v_sub_f32_e32 v4, v4, v8
	v_add_f32_e32 v4, v4, v5
	v_cvt_i32_f32_e32 v5, v8
	v_exp_f32_e32 v4, v4
	s_mov_b32 s25, 0x42ce8ed0
	v_cmp_nlt_f32_e32 vcc, s25, v1
	s_mov_b32 s25, 0xc2b17218
	v_ldexp_f32 v4, v4, v5
	v_cndmask_b32_e32 v4, 0, v4, vcc
	v_cmp_ngt_f32_e32 vcc, s25, v1
	s_nop 1
	v_cndmask_b32_e32 v1, v234, v4, vcc
	v_sub_f32_e32 v19, 1.0, v1
